# v079 + grid barrier between layer 0 out-projection and layer 1 modulation phase skipped (no data dependency; workgroup barrier kept)
# baseline (speedup 1.0000x reference)
.LBB0_418:
	s_waitcnt vmcnt(8)
	v_mov_b64_e32 v[62:63], v[98:99]
	v_mov_b64_e32 v[64:65], v[100:101]
	v_add_u32_e32 v98, 0xffffff80, v150
	v_add_u32_e32 v99, 0x80, v147
	v_cndmask_b32_e64 v98, v99, v98, s[38:39]
	v_add_u32_e32 v99, 0xffffff00, v98
	v_cmp_lt_i32_e64 s[40:41], s11, v98
	v_ashrrev_i32_e32 v99, 6, v99
	v_and_b32_e32 v98, 63, v98
	v_cndmask_b32_e32 v98, v98, v99, vcc
	v_mov_b64_e32 v[50:51], v[110:111]
	v_mov_b64_e32 v[54:55], v[106:107]
	v_mov_b64_e32 v[58:59], v[102:103]
	s_waitcnt vmcnt(7)
	v_mov_b64_e32 v[66:67], v[126:127]
	s_waitcnt vmcnt(6)
	v_mov_b64_e32 v[70:71], v[122:123]
	s_waitcnt vmcnt(5)
	v_mov_b64_e32 v[74:75], v[118:119]
	s_waitcnt vmcnt(4)
	v_mov_b64_e32 v[78:79], v[114:115]
	s_waitcnt vmcnt(3)
	v_mov_b64_e32 v[82:83], v[142:143]
	s_waitcnt vmcnt(2)
	v_mov_b64_e32 v[86:87], v[138:139]
	s_waitcnt vmcnt(1)
	v_mov_b64_e32 v[90:91], v[134:135]
	s_waitcnt vmcnt(0)
	v_mov_b64_e32 v[94:95], v[130:131]
	v_mul_lo_u32 v98, v98, s20
	v_mov_b64_e32 v[52:53], v[112:113]
	v_mov_b64_e32 v[56:57], v[108:109]
	v_mov_b64_e32 v[60:61], v[104:105]
	v_mov_b64_e32 v[68:69], v[128:129]
	v_mov_b64_e32 v[72:73], v[124:125]
	v_mov_b64_e32 v[76:77], v[120:121]
	v_mov_b64_e32 v[80:81], v[116:117]
	v_mov_b64_e32 v[84:85], v[144:145]
	v_mov_b64_e32 v[88:89], v[140:141]
	v_mov_b64_e32 v[92:93], v[136:137]
	v_mov_b64_e32 v[96:97], v[132:133]
	v_add_u32_e32 v130, s12, v98
	v_mov_b32_e32 v100, 1.0
	v_mov_b32_e32 v101, 0
	v_mov_b32_e32 v99, 0
	v_mov_b32_e32 v98, 1.0
	s_and_saveexec_b64 s[4:5], s[40:41]
	ds_read2st64_b32 v[98:99], v130 offset1:33
	s_or_b64 exec, exec, s[4:5]
	s_and_saveexec_b64 s[4:5], s[40:41]
	v_add_u32_e32 v100, 4, v130
	ds_read2st64_b32 v[100:101], v100 offset1:33
	s_or_b64 exec, exec, s[4:5]
	v_mov_b32_e32 v104, 1.0
	v_mov_b32_e32 v105, 0
	v_mov_b32_e32 v103, 0
	v_mov_b32_e32 v102, 1.0
	s_and_saveexec_b64 s[4:5], s[40:41]
	v_add_u32_e32 v102, 8, v130
	ds_read2st64_b32 v[102:103], v102 offset1:33
	s_or_b64 exec, exec, s[4:5]
	s_and_saveexec_b64 s[4:5], s[40:41]
	v_add_u32_e32 v104, 12, v130
	ds_read2st64_b32 v[104:105], v104 offset1:33
	s_or_b64 exec, exec, s[4:5]
	v_mov_b32_e32 v108, 1.0
	v_mov_b32_e32 v109, 0
	v_mov_b32_e32 v107, 0
	v_mov_b32_e32 v106, 1.0
	s_and_saveexec_b64 s[4:5], s[40:41]
	v_add_u32_e32 v106, 16, v130
	ds_read2st64_b32 v[106:107], v106 offset1:33
	s_or_b64 exec, exec, s[4:5]
	s_and_saveexec_b64 s[4:5], s[40:41]
	v_add_u32_e32 v108, 20, v130
	ds_read2st64_b32 v[108:109], v108 offset1:33
	s_or_b64 exec, exec, s[4:5]
	v_mov_b32_e32 v112, 1.0
	v_mov_b32_e32 v113, 0
	v_mov_b32_e32 v111, 0
	v_mov_b32_e32 v110, 1.0
	s_and_saveexec_b64 s[4:5], s[40:41]
	v_add_u32_e32 v110, 24, v130
	ds_read2st64_b32 v[110:111], v110 offset1:33
	s_or_b64 exec, exec, s[4:5]
	s_and_saveexec_b64 s[4:5], s[40:41]
	v_add_u32_e32 v112, 28, v130
	ds_read2st64_b32 v[112:113], v112 offset1:33
	s_or_b64 exec, exec, s[4:5]
	v_mov_b32_e32 v116, 1.0
	v_mov_b32_e32 v117, 0
	v_mov_b32_e32 v115, 0
	v_mov_b32_e32 v114, 1.0
	s_and_saveexec_b64 s[4:5], s[40:41]
	v_add_u32_e32 v114, 32, v130
	ds_read2st64_b32 v[114:115], v114 offset1:33
	s_or_b64 exec, exec, s[4:5]
	s_and_saveexec_b64 s[4:5], s[40:41]
	v_add_u32_e32 v116, 36, v130
	ds_read2st64_b32 v[116:117], v116 offset1:33
	s_or_b64 exec, exec, s[4:5]
	v_mov_b32_e32 v122, 1.0
	v_mov_b32_e32 v123, 0
	v_mov_b32_e32 v121, 0
	v_mov_b32_e32 v120, 1.0
	s_and_saveexec_b64 s[4:5], s[40:41]
	v_add_u32_e32 v118, 40, v130
	ds_read2st64_b32 v[120:121], v118 offset1:33
	s_or_b64 exec, exec, s[4:5]
	s_and_saveexec_b64 s[4:5], s[40:41]
	v_add_u32_e32 v118, 44, v130
	ds_read2st64_b32 v[122:123], v118 offset1:33
	s_or_b64 exec, exec, s[4:5]
	v_mov_b32_e32 v126, 1.0
	v_mov_b32_e32 v127, 0
	v_mov_b32_e32 v125, 0
	v_mov_b32_e32 v124, 1.0
	s_and_saveexec_b64 s[4:5], s[40:41]
	v_add_u32_e32 v118, 48, v130
	ds_read2st64_b32 v[124:125], v118 offset1:33
	s_or_b64 exec, exec, s[4:5]
	s_and_saveexec_b64 s[4:5], s[40:41]
	v_add_u32_e32 v118, 52, v130
	ds_read2st64_b32 v[126:127], v118 offset1:33
	s_or_b64 exec, exec, s[4:5]
	v_mov_b32_e32 v118, 1.0
	v_mov_b32_e32 v119, 0
	v_mov_b32_e32 v129, 0
	v_mov_b32_e32 v128, 1.0
	s_and_saveexec_b64 s[4:5], s[40:41]
	v_add_u32_e32 v128, 56, v130
	ds_read2st64_b32 v[128:129], v128 offset1:33
	s_or_b64 exec, exec, s[4:5]
	s_and_saveexec_b64 s[4:5], s[40:41]
	v_add_u32_e32 v118, 60, v130
	ds_read2st64_b32 v[118:119], v118 offset1:33
	s_or_b64 exec, exec, s[4:5]
	v_lshlrev_b32_e32 v132, 16, v45
	v_lshlrev_b32_e32 v131, 16, v37
	s_waitcnt lgkmcnt(0)
	v_mul_f32_e32 v133, v129, v132
	v_fma_f32 v133, v128, v131, -v133
	v_mul_f32_e32 v128, v128, v132
	v_fmac_f32_e32 v128, v129, v131
	v_and_b32_e32 v131, 0xffff0000, v44
	v_and_b32_e32 v129, 0xffff0000, v36
	v_mul_f32_e32 v132, v127, v131
	v_fma_f32 v132, v126, v129, -v132
	v_mul_f32_e32 v126, v126, v131
	v_lshlrev_b32_e32 v44, 16, v44
	v_fmac_f32_e32 v126, v127, v129
	v_lshlrev_b32_e32 v36, 16, v36
	v_mul_f32_e32 v127, v125, v44
	v_fma_f32 v127, v124, v36, -v127
	v_mul_f32_e32 v44, v124, v44
	v_and_b32_e32 v124, 0xffff0000, v43
	v_fmac_f32_e32 v44, v125, v36
	v_and_b32_e32 v36, 0xffff0000, v35
	v_mul_f32_e32 v125, v123, v124
	v_fma_f32 v125, v122, v36, -v125
	v_mul_f32_e32 v122, v122, v124
	v_fmac_f32_e32 v122, v123, v36
	v_lshlrev_b32_e32 v36, 16, v43
	v_lshlrev_b32_e32 v35, 16, v35
	v_mul_f32_e32 v43, v121, v36
	v_mul_f32_e32 v36, v120, v36
	v_fmac_f32_e32 v36, v121, v35
	v_fma_f32 v43, v120, v35, -v43
	v_mul_f32_e32 v120, v146, v36
	v_and_b32_e32 v36, 0xffff0000, v42
	v_and_b32_e32 v35, 0xffff0000, v34
	v_mul_f32_e32 v121, v117, v36
	v_mul_f32_e32 v36, v116, v36
	v_fma_f32 v121, v116, v35, -v121
	v_fmac_f32_e32 v36, v117, v35
	v_lshlrev_b32_e32 v35, 16, v42
	v_mul_f32_e32 v116, v146, v36
	v_lshlrev_b32_e32 v34, 16, v34
	v_mul_f32_e32 v36, v115, v35
	v_mul_f32_e32 v35, v114, v35
	v_fmac_f32_e32 v35, v115, v34
	v_fma_f32 v36, v114, v34, -v36
	v_mul_f32_e32 v115, v146, v35
	v_and_b32_e32 v35, 0xffff0000, v49
	v_mul_f32_e32 v42, v146, v36
	v_and_b32_e32 v34, 0xffff0000, v41
	v_mul_f32_e32 v36, v113, v35
	v_mul_f32_e32 v35, v112, v35
	v_fmac_f32_e32 v35, v113, v34
	v_fma_f32 v36, v112, v34, -v36
	v_mul_f32_e32 v112, v146, v35
	v_lshlrev_b32_e32 v35, 16, v49
	v_mul_f32_e32 v114, v146, v36
	v_lshlrev_b32_e32 v34, 16, v41
	v_mul_f32_e32 v36, v111, v35
	v_mul_f32_e32 v35, v110, v35
	v_fmac_f32_e32 v35, v111, v34
	v_fma_f32 v36, v110, v34, -v36
	v_mul_f32_e32 v49, v146, v35
	v_and_b32_e32 v35, 0xffff0000, v48
	v_mul_f32_e32 v41, v146, v36
	v_and_b32_e32 v34, 0xffff0000, v40
	v_mul_f32_e32 v36, v109, v35
	v_mul_f32_e32 v35, v108, v35
	v_fmac_f32_e32 v35, v109, v34
	v_fma_f32 v36, v108, v34, -v36
	v_mul_f32_e32 v108, v146, v35
	v_lshlrev_b32_e32 v35, 16, v48
	v_mul_f32_e32 v110, v146, v36
	v_lshlrev_b32_e32 v34, 16, v40
	v_mul_f32_e32 v36, v107, v35
	v_mul_f32_e32 v35, v106, v35
	v_fmac_f32_e32 v35, v107, v34
	v_fma_f32 v36, v106, v34, -v36
	v_mul_f32_e32 v48, v146, v35
	v_and_b32_e32 v35, 0xffff0000, v47
	v_mul_f32_e32 v40, v146, v36
	v_and_b32_e32 v34, 0xffff0000, v39
	v_mul_f32_e32 v36, v105, v35
	v_mul_f32_e32 v35, v104, v35
	v_fmac_f32_e32 v35, v105, v34
	v_fma_f32 v36, v104, v34, -v36
	v_mul_f32_e32 v104, v146, v35
	v_lshlrev_b32_e32 v35, 16, v47
	v_mul_f32_e32 v106, v146, v36
	v_lshlrev_b32_e32 v34, 16, v39
	v_mul_f32_e32 v36, v103, v35
	v_mul_f32_e32 v35, v102, v35
	v_fmac_f32_e32 v35, v103, v34
	v_fma_f32 v36, v102, v34, -v36
	v_mul_f32_e32 v47, v146, v35
	v_and_b32_e32 v35, 0xffff0000, v46
	v_mul_f32_e32 v39, v146, v36
	v_and_b32_e32 v34, 0xffff0000, v38
	v_mul_f32_e32 v36, v101, v35
	v_mul_f32_e32 v35, v100, v35
	v_fmac_f32_e32 v35, v101, v34
	v_fma_f32 v36, v100, v34, -v36
	v_mul_f32_e32 v100, v146, v35
	v_lshlrev_b32_e32 v35, 16, v46
	v_mul_f32_e32 v102, v146, v36
	v_lshlrev_b32_e32 v34, 16, v38
	v_mul_f32_e32 v36, v99, v35
	v_mul_f32_e32 v35, v98, v35
	v_fmac_f32_e32 v35, v99, v34
	v_fma_f32 v36, v98, v34, -v36
	v_mul_f32_e32 v46, v146, v35
	v_and_b32_e32 v35, 0xffff0000, v45
	v_and_b32_e32 v34, 0xffff0000, v37
	v_mul_f32_e32 v38, v146, v36
	s_and_b32 s0, s6, 1
	v_pk_mul_f32 v[36:37], v[118:119], v[34:35]
	v_pk_mul_f32 v[34:35], v[118:119], v[34:35] op_sel:[1,0] op_sel_hi:[0,1]
	v_sub_f32_e32 v36, v36, v37
	v_add_f32_e32 v34, v34, v35
	s_mul_i32 s0, s0, 0xcc00
	v_mul_f32_e32 v133, v146, v133
	v_mul_f32_e32 v132, v146, v132
	v_mul_f32_e32 v127, v146, v127
	v_mul_f32_e32 v125, v146, v125
	v_mul_f32_e32 v43, v146, v43
	v_mul_f32_e32 v121, v146, v121
	v_mul_f32_e32 v45, v146, v36
	v_mul_f32_e32 v98, v146, v34
	v_cvt_pk_bf16_f32 v34, v38, v102
	v_cvt_pk_bf16_f32 v35, v39, v106
	v_cvt_pk_bf16_f32 v36, v40, v110
	v_cvt_pk_bf16_f32 v37, v41, v114
	v_add_u32_e32 v114, s0, v149
	ds_write_b128 v114, v[34:37]
	v_cvt_pk_bf16_f32 v34, v42, v121
	v_cvt_pk_bf16_f32 v35, v43, v125
	v_cvt_pk_bf16_f32 v36, v127, v132
	v_cvt_pk_bf16_f32 v37, v133, v45
	v_mul_f32_e32 v128, v146, v128
	v_mul_f32_e32 v126, v146, v126
	v_mul_f32_e32 v44, v146, v44
	v_mul_f32_e32 v122, v146, v122
	ds_write_b128 v114, v[34:37] offset:16
	v_cvt_pk_bf16_f32 v34, v46, v100
	v_cvt_pk_bf16_f32 v35, v47, v104
	v_cvt_pk_bf16_f32 v36, v48, v108
	v_cvt_pk_bf16_f32 v37, v49, v112
	ds_write_b128 v114, v[34:37] offset:128
	v_cvt_pk_bf16_f32 v34, v115, v116
	v_cvt_pk_bf16_f32 v35, v120, v122
	v_cvt_pk_bf16_f32 v36, v44, v126
	v_cvt_pk_bf16_f32 v37, v128, v98
	ds_write_b128 v114, v[34:37] offset:144
	s_waitcnt lgkmcnt(0)
	s_barrier
	v_mov_b32_e32 v36, 1.0
	v_mov_b32_e32 v37, 0
	v_mov_b32_e32 v35, 0
	v_mov_b32_e32 v34, 1.0
	s_and_saveexec_b64 s[4:5], s[40:41]
	v_add_u32_e32 v34, 64, v130
	ds_read2st64_b32 v[34:35], v34 offset1:33
	s_or_b64 exec, exec, s[4:5]
	s_and_saveexec_b64 s[4:5], s[40:41]
	v_add_u32_e32 v36, 0x44, v130
	ds_read2st64_b32 v[36:37], v36 offset1:33
	s_or_b64 exec, exec, s[4:5]
	v_mov_b32_e32 v40, 1.0
	v_mov_b32_e32 v41, 0
	v_mov_b32_e32 v39, 0
	v_mov_b32_e32 v38, 1.0
	s_and_saveexec_b64 s[4:5], s[40:41]
	v_add_u32_e32 v38, 0x48, v130
	ds_read2st64_b32 v[38:39], v38 offset1:33
	s_or_b64 exec, exec, s[4:5]
	s_and_saveexec_b64 s[4:5], s[40:41]
	v_add_u32_e32 v40, 0x4c, v130
	ds_read2st64_b32 v[40:41], v40 offset1:33
	s_or_b64 exec, exec, s[4:5]
	v_mov_b32_e32 v44, 1.0
	v_mov_b32_e32 v45, 0
	v_mov_b32_e32 v43, 0
	v_mov_b32_e32 v42, 1.0
	s_and_saveexec_b64 s[4:5], s[40:41]
	v_add_u32_e32 v42, 0x50, v130
	ds_read2st64_b32 v[42:43], v42 offset1:33
	s_or_b64 exec, exec, s[4:5]
	s_and_saveexec_b64 s[4:5], s[40:41]
	v_add_u32_e32 v44, 0x54, v130
	ds_read2st64_b32 v[44:45], v44 offset1:33
	s_or_b64 exec, exec, s[4:5]
	v_mov_b32_e32 v48, 1.0
	v_mov_b32_e32 v49, 0
	v_mov_b32_e32 v47, 0
	v_mov_b32_e32 v46, 1.0
	s_and_saveexec_b64 s[4:5], s[40:41]
	v_add_u32_e32 v46, 0x58, v130
	ds_read2st64_b32 v[46:47], v46 offset1:33
	s_or_b64 exec, exec, s[4:5]
	s_and_saveexec_b64 s[4:5], s[40:41]
	v_add_u32_e32 v48, 0x5c, v130
	ds_read2st64_b32 v[48:49], v48 offset1:33
	s_or_b64 exec, exec, s[4:5]
	v_mov_b32_e32 v100, 1.0
	v_mov_b32_e32 v101, 0
	v_mov_b32_e32 v99, 0
	v_mov_b32_e32 v98, 1.0
	s_and_saveexec_b64 s[4:5], s[40:41]
	v_add_u32_e32 v98, 0x60, v130
	ds_read2st64_b32 v[98:99], v98 offset1:33
	s_or_b64 exec, exec, s[4:5]
	s_and_saveexec_b64 s[4:5], s[40:41]
	v_add_u32_e32 v100, 0x64, v130
	ds_read2st64_b32 v[100:101], v100 offset1:33
	s_or_b64 exec, exec, s[4:5]
	v_mov_b32_e32 v106, 1.0
	v_mov_b32_e32 v107, 0
	v_mov_b32_e32 v105, 0
	v_mov_b32_e32 v104, 1.0
	s_and_saveexec_b64 s[4:5], s[40:41]
	v_add_u32_e32 v102, 0x68, v130
	ds_read2st64_b32 v[104:105], v102 offset1:33
	s_or_b64 exec, exec, s[4:5]
	s_and_saveexec_b64 s[4:5], s[40:41]
	v_add_u32_e32 v102, 0x6c, v130
	ds_read2st64_b32 v[106:107], v102 offset1:33
	s_or_b64 exec, exec, s[4:5]
	v_mov_b32_e32 v110, 1.0
	v_mov_b32_e32 v111, 0
	v_mov_b32_e32 v109, 0
	v_mov_b32_e32 v108, 1.0
	s_and_saveexec_b64 s[4:5], s[40:41]
	v_add_u32_e32 v102, 0x70, v130
	ds_read2st64_b32 v[108:109], v102 offset1:33
	s_or_b64 exec, exec, s[4:5]
	s_and_saveexec_b64 s[4:5], s[40:41]
	v_add_u32_e32 v102, 0x74, v130
	ds_read2st64_b32 v[110:111], v102 offset1:33
	s_or_b64 exec, exec, s[4:5]
	v_mov_b32_e32 v102, 1.0
	v_mov_b32_e32 v103, 0
	v_mov_b32_e32 v113, 0
	v_mov_b32_e32 v112, 1.0
	s_and_saveexec_b64 s[4:5], s[40:41]
	v_add_u32_e32 v112, 0x78, v130
	ds_read2st64_b32 v[112:113], v112 offset1:33
	s_or_b64 exec, exec, s[4:5]
	s_and_saveexec_b64 s[4:5], s[40:41]
	v_add_u32_e32 v102, 0x7c, v130
	ds_read2st64_b32 v[102:103], v102 offset1:33
	s_or_b64 exec, exec, s[4:5]
	v_lshlrev_b32_e32 v116, 16, v29
	v_lshlrev_b32_e32 v115, 16, v21
	s_waitcnt lgkmcnt(0)
	v_mul_f32_e32 v117, v113, v116
	v_fma_f32 v117, v112, v115, -v117
	v_mul_f32_e32 v112, v112, v116
	v_fmac_f32_e32 v112, v113, v115
	v_and_b32_e32 v115, 0xffff0000, v28
	v_and_b32_e32 v113, 0xffff0000, v20
	v_mul_f32_e32 v116, v111, v115
	v_fma_f32 v116, v110, v113, -v116
	v_mul_f32_e32 v110, v110, v115
	v_lshlrev_b32_e32 v28, 16, v28
	v_fmac_f32_e32 v110, v111, v113
	v_lshlrev_b32_e32 v20, 16, v20
	v_mul_f32_e32 v111, v109, v28
	v_fma_f32 v111, v108, v20, -v111
	v_mul_f32_e32 v28, v108, v28
	v_and_b32_e32 v108, 0xffff0000, v27
	v_fmac_f32_e32 v28, v109, v20
	v_and_b32_e32 v20, 0xffff0000, v19
	v_mul_f32_e32 v109, v107, v108
	v_fma_f32 v109, v106, v20, -v109
	v_mul_f32_e32 v106, v106, v108
	v_fmac_f32_e32 v106, v107, v20
	v_lshlrev_b32_e32 v20, 16, v27
	v_lshlrev_b32_e32 v19, 16, v19
	v_mul_f32_e32 v27, v105, v20
	v_mul_f32_e32 v20, v104, v20
	v_fmac_f32_e32 v20, v105, v19
	v_fma_f32 v27, v104, v19, -v27
	v_mul_f32_e32 v104, v146, v20
	v_and_b32_e32 v20, 0xffff0000, v26
	v_and_b32_e32 v19, 0xffff0000, v18
	v_mul_f32_e32 v105, v101, v20
	v_mul_f32_e32 v20, v100, v20
	v_fma_f32 v105, v100, v19, -v105
	v_fmac_f32_e32 v20, v101, v19
	v_lshlrev_b32_e32 v19, 16, v26
	v_mul_f32_e32 v100, v146, v20
	v_lshlrev_b32_e32 v18, 16, v18
	v_mul_f32_e32 v20, v99, v19
	v_mul_f32_e32 v19, v98, v19
	v_fmac_f32_e32 v19, v99, v18
	v_fma_f32 v20, v98, v18, -v20
	v_mul_f32_e32 v98, v146, v19
	v_and_b32_e32 v19, 0xffff0000, v33
	v_mul_f32_e32 v26, v146, v20
	v_and_b32_e32 v18, 0xffff0000, v25
	v_mul_f32_e32 v20, v49, v19
	v_mul_f32_e32 v19, v48, v19
	v_fmac_f32_e32 v19, v49, v18
	v_fma_f32 v20, v48, v18, -v20
	v_mul_f32_e32 v48, v146, v19
	v_lshlrev_b32_e32 v19, 16, v33
	v_mul_f32_e32 v99, v146, v20
	v_lshlrev_b32_e32 v18, 16, v25
	v_mul_f32_e32 v20, v47, v19
	v_mul_f32_e32 v19, v46, v19
	v_fmac_f32_e32 v19, v47, v18
	v_fma_f32 v20, v46, v18, -v20
	v_mul_f32_e32 v33, v146, v19
	v_and_b32_e32 v19, 0xffff0000, v32
	v_mul_f32_e32 v25, v146, v20
	v_and_b32_e32 v18, 0xffff0000, v24
	v_mul_f32_e32 v20, v45, v19
	v_mul_f32_e32 v19, v44, v19
	v_fmac_f32_e32 v19, v45, v18
	v_fma_f32 v20, v44, v18, -v20
	v_mul_f32_e32 v44, v146, v19
	v_lshlrev_b32_e32 v19, 16, v32
	v_mul_f32_e32 v46, v146, v20
	v_lshlrev_b32_e32 v18, 16, v24
	v_mul_f32_e32 v20, v43, v19
	v_mul_f32_e32 v19, v42, v19
	v_fmac_f32_e32 v19, v43, v18
	v_fma_f32 v20, v42, v18, -v20
	v_mul_f32_e32 v32, v146, v19
	v_and_b32_e32 v19, 0xffff0000, v31
	v_mul_f32_e32 v24, v146, v20
	v_and_b32_e32 v18, 0xffff0000, v23
	v_mul_f32_e32 v20, v41, v19
	v_mul_f32_e32 v19, v40, v19
	v_fmac_f32_e32 v19, v41, v18
	v_fma_f32 v20, v40, v18, -v20
	v_mul_f32_e32 v40, v146, v19
	v_lshlrev_b32_e32 v19, 16, v31
	v_mul_f32_e32 v42, v146, v20
	v_lshlrev_b32_e32 v18, 16, v23
	v_mul_f32_e32 v20, v39, v19
	v_mul_f32_e32 v19, v38, v19
	v_fmac_f32_e32 v19, v39, v18
	v_fma_f32 v20, v38, v18, -v20
	v_mul_f32_e32 v31, v146, v19
	v_and_b32_e32 v19, 0xffff0000, v30
	v_mul_f32_e32 v23, v146, v20
	v_and_b32_e32 v18, 0xffff0000, v22
	v_mul_f32_e32 v20, v37, v19
	v_mul_f32_e32 v19, v36, v19
	v_fmac_f32_e32 v19, v37, v18
	v_fma_f32 v20, v36, v18, -v20
	v_mul_f32_e32 v36, v146, v19
	v_lshlrev_b32_e32 v19, 16, v30
	v_mul_f32_e32 v38, v146, v20
	v_lshlrev_b32_e32 v18, 16, v22
	v_mul_f32_e32 v20, v35, v19
	v_mul_f32_e32 v19, v34, v19
	v_fmac_f32_e32 v19, v35, v18
	v_fma_f32 v20, v34, v18, -v20
	v_mul_f32_e32 v30, v146, v19
	v_and_b32_e32 v19, 0xffff0000, v29
	v_and_b32_e32 v18, 0xffff0000, v21
	v_mul_f32_e32 v22, v146, v20
	v_pk_mul_f32 v[20:21], v[102:103], v[18:19]
	v_pk_mul_f32 v[18:19], v[102:103], v[18:19] op_sel:[1,0] op_sel_hi:[0,1]
	v_sub_f32_e32 v20, v20, v21
	v_add_f32_e32 v18, v18, v19
	v_mul_f32_e32 v117, v146, v117
	v_mul_f32_e32 v116, v146, v116
	v_mul_f32_e32 v111, v146, v111
	v_mul_f32_e32 v109, v146, v109
	v_mul_f32_e32 v27, v146, v27
	v_mul_f32_e32 v105, v146, v105
	v_mul_f32_e32 v29, v146, v20
	v_mul_f32_e32 v34, v146, v18
	v_cvt_pk_bf16_f32 v18, v22, v38
	v_cvt_pk_bf16_f32 v19, v23, v42
	v_cvt_pk_bf16_f32 v20, v24, v46
	v_cvt_pk_bf16_f32 v21, v25, v99
	ds_write_b128 v114, v[18:21] offset:32
	v_cvt_pk_bf16_f32 v18, v26, v105
	v_cvt_pk_bf16_f32 v19, v27, v109
	v_cvt_pk_bf16_f32 v20, v111, v116
	v_cvt_pk_bf16_f32 v21, v117, v29
	v_mul_f32_e32 v112, v146, v112
	v_mul_f32_e32 v110, v146, v110
	v_mul_f32_e32 v28, v146, v28
	v_mul_f32_e32 v106, v146, v106
	ds_write_b128 v114, v[18:21] offset:48
	v_cvt_pk_bf16_f32 v18, v30, v36
	v_cvt_pk_bf16_f32 v19, v31, v40
	v_cvt_pk_bf16_f32 v20, v32, v44
	v_cvt_pk_bf16_f32 v21, v33, v48
	ds_write_b128 v114, v[18:21] offset:160
	v_cvt_pk_bf16_f32 v18, v98, v100
	v_cvt_pk_bf16_f32 v19, v104, v106
	v_cvt_pk_bf16_f32 v20, v28, v110
	v_cvt_pk_bf16_f32 v21, v112, v34
	s_add_i32 s4, s6, -1
	ds_write_b128 v114, v[18:21] offset:176
	v_mov_b64_e32 v[132:133], v[96:97]
	v_mov_b64_e32 v[136:137], v[92:93]
	v_mov_b64_e32 v[140:141], v[88:89]
	v_mov_b64_e32 v[144:145], v[84:85]
	v_mov_b64_e32 v[116:117], v[80:81]
	v_mov_b64_e32 v[120:121], v[76:77]
	v_mov_b64_e32 v[124:125], v[72:73]
	v_mov_b64_e32 v[128:129], v[68:69]
	v_mov_b64_e32 v[100:101], v[64:65]
	v_mov_b64_e32 v[104:105], v[60:61]
	v_mov_b64_e32 v[108:109], v[56:57]
	v_mov_b64_e32 v[112:113], v[52:53]
	v_add_u32_e32 v18, s0, v148
	s_cmp_gt_u32 s4, 64
	v_mov_b64_e32 v[130:131], v[94:95]
	v_mov_b64_e32 v[134:135], v[90:91]
	v_mov_b64_e32 v[138:139], v[86:87]
	v_mov_b64_e32 v[142:143], v[82:83]
	v_mov_b64_e32 v[114:115], v[78:79]
	v_mov_b64_e32 v[118:119], v[74:75]
	v_mov_b64_e32 v[122:123], v[70:71]
	v_mov_b64_e32 v[126:127], v[66:67]
	v_mov_b64_e32 v[98:99], v[62:63]
	v_mov_b64_e32 v[102:103], v[58:59]
	v_mov_b64_e32 v[106:107], v[54:55]
	v_mov_b64_e32 v[110:111], v[50:51]
	ds_write_b128 v18, v[14:17] offset:34816
	ds_write_b128 v18, v[10:13] offset:34832
	ds_write_b128 v18, v[6:9] offset:34848
	ds_write_b128 v18, v[2:5] offset:34864
	s_cbranch_scc1 .LBB0_417
	v_cndmask_b32_e64 v2, v147, v150, s[38:39]
	v_add_lshl_u32 v194, v2, s84, 10
	v_lshl_add_u64 v[2:3], s[42:43], 0, v[194:195]
	v_lshl_add_u64 v[4:5], v[2:3], 0, s[88:89]
	v_lshl_add_u64 v[2:3], s[44:45], 1, v[2:3]
	global_load_dwordx4 v[110:113], v[4:5], off offset:48
	global_load_dwordx4 v[106:109], v[4:5], off offset:32
	global_load_dwordx4 v[102:105], v[4:5], off offset:16
	global_load_dwordx4 v[98:101], v[4:5], off
	global_load_dwordx4 v[126:129], v[4:5], off offset:176
	global_load_dwordx4 v[122:125], v[4:5], off offset:160
	global_load_dwordx4 v[118:121], v[4:5], off offset:144
	global_load_dwordx4 v[114:117], v[4:5], off offset:128
	global_load_dwordx4 v[142:145], v[2:3], off offset:560
	global_load_dwordx4 v[138:141], v[2:3], off offset:544
	global_load_dwordx4 v[134:137], v[2:3], off offset:528
	global_load_dwordx4 v[130:133], v[2:3], off offset:512
	s_branch .LBB0_417
.Lmy_tr10_a:
	s_branch .LBB0_10
.LBB0_484:
	s_waitcnt lgkmcnt(0)
	s_barrier
	s_waitcnt lgkmcnt(0)
	s_barrier

.LBB0_695:
	v_lshl_add_u32 v148, s6, 8, v150
	s_lshl_b32 s0, s4, 8
	v_or_b32_e32 v149, s0, v152
	v_mov_b32_e32 v181, 0
	v_lshlrev_b32_e32 v180, 11, v148
	v_lshl_add_u32 v180, v149, 1, v180
	v_lshl_add_u64 v[142:143], s[40:41], 0, v[180:181]
	v_lshlrev_b32_e32 v180, 2, v149
	v_lshl_add_u64 v[178:179], s[46:47], 0, v[180:181]
	global_load_dwordx4 v[154:157], v[178:179], off
	global_load_dwordx4 v[158:161], v[178:179], off offset:16
	global_load_dwordx4 v[162:165], v[178:179], off offset:512
	global_load_dwordx4 v[166:169], v[178:179], off offset:528
	s_add_i32 s4, s0, 0x2400
	s_ashr_i32 s0, s4, 9
	s_mul_hi_i32 s4, s0, 0x1100000
	s_mul_i32 s0, s0, 0x1100000
	s_add_u32 s58, s65, s0
	s_addc_u32 s59, s66, s4
	v_and_b32_e32 v180, 0x1ff, v149
	v_lshlrev_b32_e32 v180, 1, v180
	v_lshl_add_u32 v180, v148, 10, v180
	v_lshl_add_u64 v[144:145], s[58:59], 0, v[180:181]
	v_lshlrev_b32_e32 v180, 13, v148
	v_lshl_add_u32 v180, v149, 1, v180
	v_add_u32_e32 v180, 0x1000, v180
	v_lshl_add_u64 v[146:147], s[44:45], 0, v[180:181]
	global_load_dwordx4 v[170:173], v[142:143], off
	global_load_dwordx4 v[174:177], v[144:145], off
	s_waitcnt vmcnt(2)
	v_pk_add_f32 v[126:127], v[126:127], v[154:155]
	v_pk_add_f32 v[122:123], v[122:123], v[158:159]
	v_pk_add_f32 v[128:129], v[128:129], v[156:157]
	v_pk_add_f32 v[124:125], v[124:125], v[160:161]
	v_pk_add_f32 v[118:119], v[118:119], v[162:163]
	v_pk_add_f32 v[114:115], v[114:115], v[166:167]
	v_pk_add_f32 v[120:121], v[120:121], v[164:165]
	v_pk_add_f32 v[116:117], v[116:117], v[168:169]
	v_pk_add_f32 v[110:111], v[110:111], v[154:155]
	v_pk_add_f32 v[106:107], v[106:107], v[158:159]
	v_pk_add_f32 v[112:113], v[112:113], v[156:157]
	v_pk_add_f32 v[108:109], v[108:109], v[160:161]
	v_pk_add_f32 v[102:103], v[102:103], v[162:163]
	v_pk_add_f32 v[98:99], v[98:99], v[166:167]
	v_pk_add_f32 v[104:105], v[104:105], v[164:165]
	v_pk_add_f32 v[100:101], v[100:101], v[168:169]
	v_pk_add_f32 v[94:95], v[94:95], v[154:155]
	v_pk_add_f32 v[90:91], v[90:91], v[158:159]
	v_pk_add_f32 v[96:97], v[96:97], v[156:157]
	v_pk_add_f32 v[92:93], v[92:93], v[160:161]
	v_pk_add_f32 v[86:87], v[86:87], v[162:163]
	v_pk_add_f32 v[82:83], v[82:83], v[166:167]
	v_pk_add_f32 v[88:89], v[88:89], v[164:165]
	v_pk_add_f32 v[84:85], v[84:85], v[168:169]
	v_pk_add_f32 v[78:79], v[78:79], v[154:155]
	v_pk_add_f32 v[74:75], v[74:75], v[158:159]
	v_pk_add_f32 v[80:81], v[80:81], v[156:157]
	v_pk_add_f32 v[76:77], v[76:77], v[160:161]
	v_pk_add_f32 v[70:71], v[70:71], v[162:163]
	v_pk_add_f32 v[66:67], v[66:67], v[166:167]
	v_pk_add_f32 v[72:73], v[72:73], v[164:165]
	v_pk_add_f32 v[68:69], v[68:69], v[168:169]
	v_pk_add_f32 v[62:63], v[62:63], v[154:155]
	v_pk_add_f32 v[58:59], v[58:59], v[158:159]
	v_pk_add_f32 v[64:65], v[64:65], v[156:157]
	v_pk_add_f32 v[60:61], v[60:61], v[160:161]
	v_pk_add_f32 v[54:55], v[54:55], v[162:163]
	v_pk_add_f32 v[50:51], v[50:51], v[166:167]
	v_pk_add_f32 v[56:57], v[56:57], v[164:165]
	v_pk_add_f32 v[52:53], v[52:53], v[168:169]
	v_pk_add_f32 v[46:47], v[46:47], v[154:155]
	v_pk_add_f32 v[42:43], v[42:43], v[158:159]
	v_pk_add_f32 v[48:49], v[48:49], v[156:157]
	v_pk_add_f32 v[44:45], v[44:45], v[160:161]
	v_pk_add_f32 v[38:39], v[38:39], v[162:163]
	v_pk_add_f32 v[34:35], v[34:35], v[166:167]
	v_pk_add_f32 v[40:41], v[40:41], v[164:165]
	v_pk_add_f32 v[36:37], v[36:37], v[168:169]
	v_pk_add_f32 v[30:31], v[30:31], v[154:155]
	v_pk_add_f32 v[26:27], v[26:27], v[158:159]
	v_pk_add_f32 v[32:33], v[32:33], v[156:157]
	v_pk_add_f32 v[28:29], v[28:29], v[160:161]
	v_pk_add_f32 v[22:23], v[22:23], v[162:163]
	v_pk_add_f32 v[18:19], v[18:19], v[166:167]
	v_pk_add_f32 v[24:25], v[24:25], v[164:165]
	v_pk_add_f32 v[20:21], v[20:21], v[168:169]
	v_pk_add_f32 v[14:15], v[14:15], v[154:155]
	v_pk_add_f32 v[10:11], v[10:11], v[158:159]
	v_pk_add_f32 v[16:17], v[16:17], v[156:157]
	v_pk_add_f32 v[12:13], v[12:13], v[160:161]
	v_pk_add_f32 v[6:7], v[6:7], v[162:163]
	v_pk_add_f32 v[2:3], v[2:3], v[166:167]
	v_pk_add_f32 v[8:9], v[8:9], v[164:165]
	v_pk_add_f32 v[4:5], v[4:5], v[168:169]
	global_load_dwordx4 v[154:157], v[142:143], off offset:256
	global_load_dwordx4 v[158:161], v[144:145], off offset:256
	s_mov_b64 s[58:59], 0x8000
	v_lshl_add_u64 v[142:143], v[142:143], 0, s[58:59]
	s_mov_b64 s[58:59], 0x4000
	v_lshl_add_u64 v[144:145], v[144:145], 0, s[58:59]
	global_load_dwordx4 v[162:165], v[142:143], off
	global_load_dwordx4 v[166:169], v[144:145], off
	s_waitcnt vmcnt(4)
	v_lshlrev_b32_e32 v178, 16, v170
	v_and_b32_e32 v170, 0xffff0000, v170
	v_lshlrev_b32_e32 v179, 16, v174
	v_and_b32_e32 v174, 0xffff0000, v174
	v_mul_f32_e32 v126, 0xbfb8aa3b, v126
	v_mul_f32_e32 v127, 0xbfb8aa3b, v127
	v_mul_f32_e32 v180, 0xbfb8aa3b, v179
	v_mul_f32_e32 v181, 0xbfb8aa3b, v174
	v_exp_f32_e32 v126, v126
	v_exp_f32_e32 v127, v127
	v_exp_f32_e32 v180, v180
	v_exp_f32_e32 v181, v181
	v_add_f32_e32 v126, 1.0, v126
	v_add_f32_e32 v127, 1.0, v127
	v_add_f32_e32 v180, 1.0, v180
	v_add_f32_e32 v181, 1.0, v181
	v_rcp_f32_e32 v126, v126
	v_rcp_f32_e32 v127, v127
	v_rcp_f32_e32 v180, v180
	v_rcp_f32_e32 v181, v181
	v_mul_f32_e32 v126, v126, v178
	v_mul_f32_e32 v127, v127, v170
	v_mul_f32_e32 v180, v180, v179
	v_mul_f32_e32 v181, v181, v174
	v_mul_f32_e32 v126, v126, v180
	v_mul_f32_e32 v127, v127, v181
	v_lshlrev_b32_e32 v178, 16, v171
	v_and_b32_e32 v171, 0xffff0000, v171
	v_lshlrev_b32_e32 v179, 16, v175
	v_and_b32_e32 v175, 0xffff0000, v175
	v_mul_f32_e32 v128, 0xbfb8aa3b, v128
	v_mul_f32_e32 v129, 0xbfb8aa3b, v129
	v_mul_f32_e32 v180, 0xbfb8aa3b, v179
	v_mul_f32_e32 v181, 0xbfb8aa3b, v175
	v_exp_f32_e32 v128, v128
	v_exp_f32_e32 v129, v129
	v_exp_f32_e32 v180, v180
	v_exp_f32_e32 v181, v181
	v_add_f32_e32 v128, 1.0, v128
	v_add_f32_e32 v129, 1.0, v129
	v_add_f32_e32 v180, 1.0, v180
	v_add_f32_e32 v181, 1.0, v181
	v_rcp_f32_e32 v128, v128
	v_rcp_f32_e32 v129, v129
	v_rcp_f32_e32 v180, v180
	v_rcp_f32_e32 v181, v181
	v_mul_f32_e32 v128, v128, v178
	v_mul_f32_e32 v129, v129, v171
	v_mul_f32_e32 v180, v180, v179
	v_mul_f32_e32 v181, v181, v175
	v_mul_f32_e32 v128, v128, v180
	v_mul_f32_e32 v129, v129, v181
	v_lshlrev_b32_e32 v178, 16, v172
	v_and_b32_e32 v172, 0xffff0000, v172
	v_lshlrev_b32_e32 v179, 16, v176
	v_and_b32_e32 v176, 0xffff0000, v176
	v_mul_f32_e32 v122, 0xbfb8aa3b, v122
	v_mul_f32_e32 v123, 0xbfb8aa3b, v123
	v_mul_f32_e32 v180, 0xbfb8aa3b, v179
	v_mul_f32_e32 v181, 0xbfb8aa3b, v176
	v_exp_f32_e32 v122, v122
	v_exp_f32_e32 v123, v123
	v_exp_f32_e32 v180, v180
	v_exp_f32_e32 v181, v181
	v_add_f32_e32 v122, 1.0, v122
	v_add_f32_e32 v123, 1.0, v123
	v_add_f32_e32 v180, 1.0, v180
	v_add_f32_e32 v181, 1.0, v181
	v_rcp_f32_e32 v122, v122
	v_rcp_f32_e32 v123, v123
	v_rcp_f32_e32 v180, v180
	v_rcp_f32_e32 v181, v181
	v_mul_f32_e32 v122, v122, v178
	v_mul_f32_e32 v123, v123, v172
	v_mul_f32_e32 v180, v180, v179
	v_mul_f32_e32 v181, v181, v176
	v_mul_f32_e32 v122, v122, v180
	v_mul_f32_e32 v123, v123, v181
	v_lshlrev_b32_e32 v178, 16, v173
	v_and_b32_e32 v173, 0xffff0000, v173
	v_lshlrev_b32_e32 v179, 16, v177
	v_and_b32_e32 v177, 0xffff0000, v177
	v_mul_f32_e32 v124, 0xbfb8aa3b, v124
	v_mul_f32_e32 v125, 0xbfb8aa3b, v125
	v_mul_f32_e32 v180, 0xbfb8aa3b, v179
	v_mul_f32_e32 v181, 0xbfb8aa3b, v177
	v_exp_f32_e32 v124, v124
	v_exp_f32_e32 v125, v125
	v_exp_f32_e32 v180, v180
	v_exp_f32_e32 v181, v181
	v_add_f32_e32 v124, 1.0, v124
	v_add_f32_e32 v125, 1.0, v125
	v_add_f32_e32 v180, 1.0, v180
	v_add_f32_e32 v181, 1.0, v181
	v_rcp_f32_e32 v124, v124
	v_rcp_f32_e32 v125, v125
	v_rcp_f32_e32 v180, v180
	v_rcp_f32_e32 v181, v181
	v_mul_f32_e32 v124, v124, v178
	v_mul_f32_e32 v125, v125, v173
	v_mul_f32_e32 v180, v180, v179
	v_mul_f32_e32 v181, v181, v177
	v_mul_f32_e32 v124, v124, v180
	v_mul_f32_e32 v125, v125, v181
	v_cvt_pk_bf16_f32 v126, v126, v127
	v_cvt_pk_bf16_f32 v127, v128, v129
	v_cvt_pk_bf16_f32 v128, v122, v123
	v_cvt_pk_bf16_f32 v129, v124, v125
	global_store_dwordx4 v[146:147], v[126:129], off
	global_load_dwordx4 v[170:173], v[142:143], off offset:256
	global_load_dwordx4 v[174:177], v[144:145], off offset:256
	s_waitcnt vmcnt(5)
	v_lshlrev_b32_e32 v178, 16, v154
	v_and_b32_e32 v154, 0xffff0000, v154
	v_lshlrev_b32_e32 v179, 16, v158
	v_and_b32_e32 v158, 0xffff0000, v158
	v_mul_f32_e32 v118, 0xbfb8aa3b, v118
	v_mul_f32_e32 v119, 0xbfb8aa3b, v119
	v_mul_f32_e32 v180, 0xbfb8aa3b, v179
	v_mul_f32_e32 v181, 0xbfb8aa3b, v158
	v_exp_f32_e32 v118, v118
	v_exp_f32_e32 v119, v119
	v_exp_f32_e32 v180, v180
	v_exp_f32_e32 v181, v181
	v_add_f32_e32 v118, 1.0, v118
	v_add_f32_e32 v119, 1.0, v119
	v_add_f32_e32 v180, 1.0, v180
	v_add_f32_e32 v181, 1.0, v181
	v_rcp_f32_e32 v118, v118
	v_rcp_f32_e32 v119, v119
	v_rcp_f32_e32 v180, v180
	v_rcp_f32_e32 v181, v181
	v_mul_f32_e32 v118, v118, v178
	v_mul_f32_e32 v119, v119, v154
	v_mul_f32_e32 v180, v180, v179
	v_mul_f32_e32 v181, v181, v158
	v_mul_f32_e32 v118, v118, v180
	v_mul_f32_e32 v119, v119, v181
	v_lshlrev_b32_e32 v178, 16, v155
	v_and_b32_e32 v155, 0xffff0000, v155
	v_lshlrev_b32_e32 v179, 16, v159
	v_and_b32_e32 v159, 0xffff0000, v159
	v_mul_f32_e32 v120, 0xbfb8aa3b, v120
	v_mul_f32_e32 v121, 0xbfb8aa3b, v121
	v_mul_f32_e32 v180, 0xbfb8aa3b, v179
	v_mul_f32_e32 v181, 0xbfb8aa3b, v159
	v_exp_f32_e32 v120, v120
	v_exp_f32_e32 v121, v121
	v_exp_f32_e32 v180, v180
	v_exp_f32_e32 v181, v181
	v_add_f32_e32 v120, 1.0, v120
	v_add_f32_e32 v121, 1.0, v121
	v_add_f32_e32 v180, 1.0, v180
	v_add_f32_e32 v181, 1.0, v181
	v_rcp_f32_e32 v120, v120
	v_rcp_f32_e32 v121, v121
	v_rcp_f32_e32 v180, v180
	v_rcp_f32_e32 v181, v181
	v_mul_f32_e32 v120, v120, v178
	v_mul_f32_e32 v121, v121, v155
	v_mul_f32_e32 v180, v180, v179
	v_mul_f32_e32 v181, v181, v159
	v_mul_f32_e32 v120, v120, v180
	v_mul_f32_e32 v121, v121, v181
	v_lshlrev_b32_e32 v178, 16, v156
	v_and_b32_e32 v156, 0xffff0000, v156
	v_lshlrev_b32_e32 v179, 16, v160
	v_and_b32_e32 v160, 0xffff0000, v160
	v_mul_f32_e32 v114, 0xbfb8aa3b, v114
	v_mul_f32_e32 v115, 0xbfb8aa3b, v115
	v_mul_f32_e32 v180, 0xbfb8aa3b, v179
	v_mul_f32_e32 v181, 0xbfb8aa3b, v160
	v_exp_f32_e32 v114, v114
	v_exp_f32_e32 v115, v115
	v_exp_f32_e32 v180, v180
	v_exp_f32_e32 v181, v181
	v_add_f32_e32 v114, 1.0, v114
	v_add_f32_e32 v115, 1.0, v115
	v_add_f32_e32 v180, 1.0, v180
	v_add_f32_e32 v181, 1.0, v181
	v_rcp_f32_e32 v114, v114
	v_rcp_f32_e32 v115, v115
	v_rcp_f32_e32 v180, v180
	v_rcp_f32_e32 v181, v181
	v_mul_f32_e32 v114, v114, v178
	v_mul_f32_e32 v115, v115, v156
	v_mul_f32_e32 v180, v180, v179
	v_mul_f32_e32 v181, v181, v160
	v_mul_f32_e32 v114, v114, v180
	v_mul_f32_e32 v115, v115, v181
	v_lshlrev_b32_e32 v178, 16, v157
	v_and_b32_e32 v157, 0xffff0000, v157
	v_lshlrev_b32_e32 v179, 16, v161
	v_and_b32_e32 v161, 0xffff0000, v161
	v_mul_f32_e32 v116, 0xbfb8aa3b, v116
	v_mul_f32_e32 v117, 0xbfb8aa3b, v117
	v_mul_f32_e32 v180, 0xbfb8aa3b, v179
	v_mul_f32_e32 v181, 0xbfb8aa3b, v161
	v_exp_f32_e32 v116, v116
	v_exp_f32_e32 v117, v117
	v_exp_f32_e32 v180, v180
	v_exp_f32_e32 v181, v181
	v_add_f32_e32 v116, 1.0, v116
	v_add_f32_e32 v117, 1.0, v117
	v_add_f32_e32 v180, 1.0, v180
	v_add_f32_e32 v181, 1.0, v181
	v_rcp_f32_e32 v116, v116
	v_rcp_f32_e32 v117, v117
	v_rcp_f32_e32 v180, v180
	v_rcp_f32_e32 v181, v181
	v_mul_f32_e32 v116, v116, v178
	v_mul_f32_e32 v117, v117, v157
	v_mul_f32_e32 v180, v180, v179
	v_mul_f32_e32 v181, v181, v161
	v_mul_f32_e32 v116, v116, v180
	v_mul_f32_e32 v117, v117, v181
	v_cvt_pk_bf16_f32 v118, v118, v119
	v_cvt_pk_bf16_f32 v119, v120, v121
	v_cvt_pk_bf16_f32 v120, v114, v115
	v_cvt_pk_bf16_f32 v121, v116, v117
	global_store_dwordx4 v[146:147], v[118:121], off offset:256
	s_mov_b64 s[58:59], 0x20000
	v_lshl_add_u64 v[146:147], v[146:147], 0, s[58:59]
	s_mov_b64 s[58:59], 0x8000
	v_lshl_add_u64 v[142:143], v[142:143], 0, s[58:59]
	s_mov_b64 s[58:59], 0x4000
	v_lshl_add_u64 v[144:145], v[144:145], 0, s[58:59]
	global_load_dwordx4 v[154:157], v[142:143], off
	global_load_dwordx4 v[158:161], v[144:145], off
	s_waitcnt vmcnt(6)
	v_lshlrev_b32_e32 v178, 16, v162
	v_and_b32_e32 v162, 0xffff0000, v162
	v_lshlrev_b32_e32 v179, 16, v166
	v_and_b32_e32 v166, 0xffff0000, v166
	v_mul_f32_e32 v110, 0xbfb8aa3b, v110
	v_mul_f32_e32 v111, 0xbfb8aa3b, v111
	v_mul_f32_e32 v180, 0xbfb8aa3b, v179
	v_mul_f32_e32 v181, 0xbfb8aa3b, v166
	v_exp_f32_e32 v110, v110
	v_exp_f32_e32 v111, v111
	v_exp_f32_e32 v180, v180
	v_exp_f32_e32 v181, v181
	v_add_f32_e32 v110, 1.0, v110
	v_add_f32_e32 v111, 1.0, v111
	v_add_f32_e32 v180, 1.0, v180
	v_add_f32_e32 v181, 1.0, v181
	v_rcp_f32_e32 v110, v110
	v_rcp_f32_e32 v111, v111
	v_rcp_f32_e32 v180, v180
	v_rcp_f32_e32 v181, v181
	v_mul_f32_e32 v110, v110, v178
	v_mul_f32_e32 v111, v111, v162
	v_mul_f32_e32 v180, v180, v179
	v_mul_f32_e32 v181, v181, v166
	v_mul_f32_e32 v110, v110, v180
	v_mul_f32_e32 v111, v111, v181
	v_lshlrev_b32_e32 v178, 16, v163
	v_and_b32_e32 v163, 0xffff0000, v163
	v_lshlrev_b32_e32 v179, 16, v167
	v_and_b32_e32 v167, 0xffff0000, v167
	v_mul_f32_e32 v112, 0xbfb8aa3b, v112
	v_mul_f32_e32 v113, 0xbfb8aa3b, v113
	v_mul_f32_e32 v180, 0xbfb8aa3b, v179
	v_mul_f32_e32 v181, 0xbfb8aa3b, v167
	v_exp_f32_e32 v112, v112
	v_exp_f32_e32 v113, v113
	v_exp_f32_e32 v180, v180
	v_exp_f32_e32 v181, v181
	v_add_f32_e32 v112, 1.0, v112
	v_add_f32_e32 v113, 1.0, v113
	v_add_f32_e32 v180, 1.0, v180
	v_add_f32_e32 v181, 1.0, v181
	v_rcp_f32_e32 v112, v112
	v_rcp_f32_e32 v113, v113
	v_rcp_f32_e32 v180, v180
	v_rcp_f32_e32 v181, v181
	v_mul_f32_e32 v112, v112, v178
	v_mul_f32_e32 v113, v113, v163
	v_mul_f32_e32 v180, v180, v179
	v_mul_f32_e32 v181, v181, v167
	v_mul_f32_e32 v112, v112, v180
	v_mul_f32_e32 v113, v113, v181
	v_lshlrev_b32_e32 v178, 16, v164
	v_and_b32_e32 v164, 0xffff0000, v164
	v_lshlrev_b32_e32 v179, 16, v168
	v_and_b32_e32 v168, 0xffff0000, v168
	v_mul_f32_e32 v106, 0xbfb8aa3b, v106
	v_mul_f32_e32 v107, 0xbfb8aa3b, v107
	v_mul_f32_e32 v180, 0xbfb8aa3b, v179
	v_mul_f32_e32 v181, 0xbfb8aa3b, v168
	v_exp_f32_e32 v106, v106
	v_exp_f32_e32 v107, v107
	v_exp_f32_e32 v180, v180
	v_exp_f32_e32 v181, v181
	v_add_f32_e32 v106, 1.0, v106
	v_add_f32_e32 v107, 1.0, v107
	v_add_f32_e32 v180, 1.0, v180
	v_add_f32_e32 v181, 1.0, v181
	v_rcp_f32_e32 v106, v106
	v_rcp_f32_e32 v107, v107
	v_rcp_f32_e32 v180, v180
	v_rcp_f32_e32 v181, v181
	v_mul_f32_e32 v106, v106, v178
	v_mul_f32_e32 v107, v107, v164
	v_mul_f32_e32 v180, v180, v179
	v_mul_f32_e32 v181, v181, v168
	v_mul_f32_e32 v106, v106, v180
	v_mul_f32_e32 v107, v107, v181
	v_lshlrev_b32_e32 v178, 16, v165
	v_and_b32_e32 v165, 0xffff0000, v165
	v_lshlrev_b32_e32 v179, 16, v169
	v_and_b32_e32 v169, 0xffff0000, v169
	v_mul_f32_e32 v108, 0xbfb8aa3b, v108
	v_mul_f32_e32 v109, 0xbfb8aa3b, v109
	v_mul_f32_e32 v180, 0xbfb8aa3b, v179
	v_mul_f32_e32 v181, 0xbfb8aa3b, v169
	v_exp_f32_e32 v108, v108
	v_exp_f32_e32 v109, v109
	v_exp_f32_e32 v180, v180
	v_exp_f32_e32 v181, v181
	v_add_f32_e32 v108, 1.0, v108
	v_add_f32_e32 v109, 1.0, v109
	v_add_f32_e32 v180, 1.0, v180
	v_add_f32_e32 v181, 1.0, v181
	v_rcp_f32_e32 v108, v108
	v_rcp_f32_e32 v109, v109
	v_rcp_f32_e32 v180, v180
	v_rcp_f32_e32 v181, v181
	v_mul_f32_e32 v108, v108, v178
	v_mul_f32_e32 v109, v109, v165
	v_mul_f32_e32 v180, v180, v179
	v_mul_f32_e32 v181, v181, v169
	v_mul_f32_e32 v108, v108, v180
	v_mul_f32_e32 v109, v109, v181
	v_cvt_pk_bf16_f32 v110, v110, v111
	v_cvt_pk_bf16_f32 v111, v112, v113
	v_cvt_pk_bf16_f32 v112, v106, v107
	v_cvt_pk_bf16_f32 v113, v108, v109
	global_store_dwordx4 v[146:147], v[110:113], off
	global_load_dwordx4 v[162:165], v[142:143], off offset:256
	global_load_dwordx4 v[166:169], v[144:145], off offset:256
	s_waitcnt vmcnt(6)
	v_lshlrev_b32_e32 v178, 16, v170
	v_and_b32_e32 v170, 0xffff0000, v170
	v_lshlrev_b32_e32 v179, 16, v174
	v_and_b32_e32 v174, 0xffff0000, v174
	v_mul_f32_e32 v102, 0xbfb8aa3b, v102
	v_mul_f32_e32 v103, 0xbfb8aa3b, v103
	v_mul_f32_e32 v180, 0xbfb8aa3b, v179
	v_mul_f32_e32 v181, 0xbfb8aa3b, v174
	v_exp_f32_e32 v102, v102
	v_exp_f32_e32 v103, v103
	v_exp_f32_e32 v180, v180
	v_exp_f32_e32 v181, v181
	v_add_f32_e32 v102, 1.0, v102
	v_add_f32_e32 v103, 1.0, v103
	v_add_f32_e32 v180, 1.0, v180
	v_add_f32_e32 v181, 1.0, v181
	v_rcp_f32_e32 v102, v102
	v_rcp_f32_e32 v103, v103
	v_rcp_f32_e32 v180, v180
	v_rcp_f32_e32 v181, v181
	v_mul_f32_e32 v102, v102, v178
	v_mul_f32_e32 v103, v103, v170
	v_mul_f32_e32 v180, v180, v179
	v_mul_f32_e32 v181, v181, v174
	v_mul_f32_e32 v102, v102, v180
	v_mul_f32_e32 v103, v103, v181
	v_lshlrev_b32_e32 v178, 16, v171
	v_and_b32_e32 v171, 0xffff0000, v171
	v_lshlrev_b32_e32 v179, 16, v175
	v_and_b32_e32 v175, 0xffff0000, v175
	v_mul_f32_e32 v104, 0xbfb8aa3b, v104
	v_mul_f32_e32 v105, 0xbfb8aa3b, v105
	v_mul_f32_e32 v180, 0xbfb8aa3b, v179
	v_mul_f32_e32 v181, 0xbfb8aa3b, v175
	v_exp_f32_e32 v104, v104
	v_exp_f32_e32 v105, v105
	v_exp_f32_e32 v180, v180
	v_exp_f32_e32 v181, v181
	v_add_f32_e32 v104, 1.0, v104
	v_add_f32_e32 v105, 1.0, v105
	v_add_f32_e32 v180, 1.0, v180
	v_add_f32_e32 v181, 1.0, v181
	v_rcp_f32_e32 v104, v104
	v_rcp_f32_e32 v105, v105
	v_rcp_f32_e32 v180, v180
	v_rcp_f32_e32 v181, v181
	v_mul_f32_e32 v104, v104, v178
	v_mul_f32_e32 v105, v105, v171
	v_mul_f32_e32 v180, v180, v179
	v_mul_f32_e32 v181, v181, v175
	v_mul_f32_e32 v104, v104, v180
	v_mul_f32_e32 v105, v105, v181
	v_lshlrev_b32_e32 v178, 16, v172
	v_and_b32_e32 v172, 0xffff0000, v172
	v_lshlrev_b32_e32 v179, 16, v176
	v_and_b32_e32 v176, 0xffff0000, v176
	v_mul_f32_e32 v98, 0xbfb8aa3b, v98
	v_mul_f32_e32 v99, 0xbfb8aa3b, v99
	v_mul_f32_e32 v180, 0xbfb8aa3b, v179
	v_mul_f32_e32 v181, 0xbfb8aa3b, v176
	v_exp_f32_e32 v98, v98
	v_exp_f32_e32 v99, v99
	v_exp_f32_e32 v180, v180
	v_exp_f32_e32 v181, v181
	v_add_f32_e32 v98, 1.0, v98
	v_add_f32_e32 v99, 1.0, v99
	v_add_f32_e32 v180, 1.0, v180
	v_add_f32_e32 v181, 1.0, v181
	v_rcp_f32_e32 v98, v98
	v_rcp_f32_e32 v99, v99
	v_rcp_f32_e32 v180, v180
	v_rcp_f32_e32 v181, v181
	v_mul_f32_e32 v98, v98, v178
	v_mul_f32_e32 v99, v99, v172
	v_mul_f32_e32 v180, v180, v179
	v_mul_f32_e32 v181, v181, v176
	v_mul_f32_e32 v98, v98, v180
	v_mul_f32_e32 v99, v99, v181
	v_lshlrev_b32_e32 v178, 16, v173
	v_and_b32_e32 v173, 0xffff0000, v173
	v_lshlrev_b32_e32 v179, 16, v177
	v_and_b32_e32 v177, 0xffff0000, v177
	v_mul_f32_e32 v100, 0xbfb8aa3b, v100
	v_mul_f32_e32 v101, 0xbfb8aa3b, v101
	v_mul_f32_e32 v180, 0xbfb8aa3b, v179
	v_mul_f32_e32 v181, 0xbfb8aa3b, v177
	v_exp_f32_e32 v100, v100
	v_exp_f32_e32 v101, v101
	v_exp_f32_e32 v180, v180
	v_exp_f32_e32 v181, v181
	v_add_f32_e32 v100, 1.0, v100
	v_add_f32_e32 v101, 1.0, v101
	v_add_f32_e32 v180, 1.0, v180
	v_add_f32_e32 v181, 1.0, v181
	v_rcp_f32_e32 v100, v100
	v_rcp_f32_e32 v101, v101
	v_rcp_f32_e32 v180, v180
	v_rcp_f32_e32 v181, v181
	v_mul_f32_e32 v100, v100, v178
	v_mul_f32_e32 v101, v101, v173
	v_mul_f32_e32 v180, v180, v179
	v_mul_f32_e32 v181, v181, v177
	v_mul_f32_e32 v100, v100, v180
	v_mul_f32_e32 v101, v101, v181
	v_cvt_pk_bf16_f32 v102, v102, v103
	v_cvt_pk_bf16_f32 v103, v104, v105
	v_cvt_pk_bf16_f32 v104, v98, v99
	v_cvt_pk_bf16_f32 v105, v100, v101
	global_store_dwordx4 v[146:147], v[102:105], off offset:256
	s_mov_b64 s[58:59], 0x20000
	v_lshl_add_u64 v[146:147], v[146:147], 0, s[58:59]
	s_mov_b64 s[58:59], 0x8000
	v_lshl_add_u64 v[142:143], v[142:143], 0, s[58:59]
	s_mov_b64 s[58:59], 0x4000
	v_lshl_add_u64 v[144:145], v[144:145], 0, s[58:59]
	global_load_dwordx4 v[170:173], v[142:143], off
	global_load_dwordx4 v[174:177], v[144:145], off
	s_waitcnt vmcnt(6)
	v_lshlrev_b32_e32 v178, 16, v154
	v_and_b32_e32 v154, 0xffff0000, v154
	v_lshlrev_b32_e32 v179, 16, v158
	v_and_b32_e32 v158, 0xffff0000, v158
	v_mul_f32_e32 v94, 0xbfb8aa3b, v94
	v_mul_f32_e32 v95, 0xbfb8aa3b, v95
	v_mul_f32_e32 v180, 0xbfb8aa3b, v179
	v_mul_f32_e32 v181, 0xbfb8aa3b, v158
	v_exp_f32_e32 v94, v94
	v_exp_f32_e32 v95, v95
	v_exp_f32_e32 v180, v180
	v_exp_f32_e32 v181, v181
	v_add_f32_e32 v94, 1.0, v94
	v_add_f32_e32 v95, 1.0, v95
	v_add_f32_e32 v180, 1.0, v180
	v_add_f32_e32 v181, 1.0, v181
	v_rcp_f32_e32 v94, v94
	v_rcp_f32_e32 v95, v95
	v_rcp_f32_e32 v180, v180
	v_rcp_f32_e32 v181, v181
	v_mul_f32_e32 v94, v94, v178
	v_mul_f32_e32 v95, v95, v154
	v_mul_f32_e32 v180, v180, v179
	v_mul_f32_e32 v181, v181, v158
	v_mul_f32_e32 v94, v94, v180
	v_mul_f32_e32 v95, v95, v181
	v_lshlrev_b32_e32 v178, 16, v155
	v_and_b32_e32 v155, 0xffff0000, v155
	v_lshlrev_b32_e32 v179, 16, v159
	v_and_b32_e32 v159, 0xffff0000, v159
	v_mul_f32_e32 v96, 0xbfb8aa3b, v96
	v_mul_f32_e32 v97, 0xbfb8aa3b, v97
	v_mul_f32_e32 v180, 0xbfb8aa3b, v179
	v_mul_f32_e32 v181, 0xbfb8aa3b, v159
	v_exp_f32_e32 v96, v96
	v_exp_f32_e32 v97, v97
	v_exp_f32_e32 v180, v180
	v_exp_f32_e32 v181, v181
	v_add_f32_e32 v96, 1.0, v96
	v_add_f32_e32 v97, 1.0, v97
	v_add_f32_e32 v180, 1.0, v180
	v_add_f32_e32 v181, 1.0, v181
	v_rcp_f32_e32 v96, v96
	v_rcp_f32_e32 v97, v97
	v_rcp_f32_e32 v180, v180
	v_rcp_f32_e32 v181, v181
	v_mul_f32_e32 v96, v96, v178
	v_mul_f32_e32 v97, v97, v155
	v_mul_f32_e32 v180, v180, v179
	v_mul_f32_e32 v181, v181, v159
	v_mul_f32_e32 v96, v96, v180
	v_mul_f32_e32 v97, v97, v181
	v_lshlrev_b32_e32 v178, 16, v156
	v_and_b32_e32 v156, 0xffff0000, v156
	v_lshlrev_b32_e32 v179, 16, v160
	v_and_b32_e32 v160, 0xffff0000, v160
	v_mul_f32_e32 v90, 0xbfb8aa3b, v90
	v_mul_f32_e32 v91, 0xbfb8aa3b, v91
	v_mul_f32_e32 v180, 0xbfb8aa3b, v179
	v_mul_f32_e32 v181, 0xbfb8aa3b, v160
	v_exp_f32_e32 v90, v90
	v_exp_f32_e32 v91, v91
	v_exp_f32_e32 v180, v180
	v_exp_f32_e32 v181, v181
	v_add_f32_e32 v90, 1.0, v90
	v_add_f32_e32 v91, 1.0, v91
	v_add_f32_e32 v180, 1.0, v180
	v_add_f32_e32 v181, 1.0, v181
	v_rcp_f32_e32 v90, v90
	v_rcp_f32_e32 v91, v91
	v_rcp_f32_e32 v180, v180
	v_rcp_f32_e32 v181, v181
	v_mul_f32_e32 v90, v90, v178
	v_mul_f32_e32 v91, v91, v156
	v_mul_f32_e32 v180, v180, v179
	v_mul_f32_e32 v181, v181, v160
	v_mul_f32_e32 v90, v90, v180
	v_mul_f32_e32 v91, v91, v181
	v_lshlrev_b32_e32 v178, 16, v157
	v_and_b32_e32 v157, 0xffff0000, v157
	v_lshlrev_b32_e32 v179, 16, v161
	v_and_b32_e32 v161, 0xffff0000, v161
	v_mul_f32_e32 v92, 0xbfb8aa3b, v92
	v_mul_f32_e32 v93, 0xbfb8aa3b, v93
	v_mul_f32_e32 v180, 0xbfb8aa3b, v179
	v_mul_f32_e32 v181, 0xbfb8aa3b, v161
	v_exp_f32_e32 v92, v92
	v_exp_f32_e32 v93, v93
	v_exp_f32_e32 v180, v180
	v_exp_f32_e32 v181, v181
	v_add_f32_e32 v92, 1.0, v92
	v_add_f32_e32 v93, 1.0, v93
	v_add_f32_e32 v180, 1.0, v180
	v_add_f32_e32 v181, 1.0, v181
	v_rcp_f32_e32 v92, v92
	v_rcp_f32_e32 v93, v93
	v_rcp_f32_e32 v180, v180
	v_rcp_f32_e32 v181, v181
	v_mul_f32_e32 v92, v92, v178
	v_mul_f32_e32 v93, v93, v157
	v_mul_f32_e32 v180, v180, v179
	v_mul_f32_e32 v181, v181, v161
	v_mul_f32_e32 v92, v92, v180
	v_mul_f32_e32 v93, v93, v181
	v_cvt_pk_bf16_f32 v94, v94, v95
	v_cvt_pk_bf16_f32 v95, v96, v97
	v_cvt_pk_bf16_f32 v96, v90, v91
	v_cvt_pk_bf16_f32 v97, v92, v93
	global_store_dwordx4 v[146:147], v[94:97], off
	global_load_dwordx4 v[154:157], v[142:143], off offset:256
	global_load_dwordx4 v[158:161], v[144:145], off offset:256
	s_waitcnt vmcnt(6)
	v_lshlrev_b32_e32 v178, 16, v162
	v_and_b32_e32 v162, 0xffff0000, v162
	v_lshlrev_b32_e32 v179, 16, v166
	v_and_b32_e32 v166, 0xffff0000, v166
	v_mul_f32_e32 v86, 0xbfb8aa3b, v86
	v_mul_f32_e32 v87, 0xbfb8aa3b, v87
	v_mul_f32_e32 v180, 0xbfb8aa3b, v179
	v_mul_f32_e32 v181, 0xbfb8aa3b, v166
	v_exp_f32_e32 v86, v86
	v_exp_f32_e32 v87, v87
	v_exp_f32_e32 v180, v180
	v_exp_f32_e32 v181, v181
	v_add_f32_e32 v86, 1.0, v86
	v_add_f32_e32 v87, 1.0, v87
	v_add_f32_e32 v180, 1.0, v180
	v_add_f32_e32 v181, 1.0, v181
	v_rcp_f32_e32 v86, v86
	v_rcp_f32_e32 v87, v87
	v_rcp_f32_e32 v180, v180
	v_rcp_f32_e32 v181, v181
	v_mul_f32_e32 v86, v86, v178
	v_mul_f32_e32 v87, v87, v162
	v_mul_f32_e32 v180, v180, v179
	v_mul_f32_e32 v181, v181, v166
	v_mul_f32_e32 v86, v86, v180
	v_mul_f32_e32 v87, v87, v181
	v_lshlrev_b32_e32 v178, 16, v163
	v_and_b32_e32 v163, 0xffff0000, v163
	v_lshlrev_b32_e32 v179, 16, v167
	v_and_b32_e32 v167, 0xffff0000, v167
	v_mul_f32_e32 v88, 0xbfb8aa3b, v88
	v_mul_f32_e32 v89, 0xbfb8aa3b, v89
	v_mul_f32_e32 v180, 0xbfb8aa3b, v179
	v_mul_f32_e32 v181, 0xbfb8aa3b, v167
	v_exp_f32_e32 v88, v88
	v_exp_f32_e32 v89, v89
	v_exp_f32_e32 v180, v180
	v_exp_f32_e32 v181, v181
	v_add_f32_e32 v88, 1.0, v88
	v_add_f32_e32 v89, 1.0, v89
	v_add_f32_e32 v180, 1.0, v180
	v_add_f32_e32 v181, 1.0, v181
	v_rcp_f32_e32 v88, v88
	v_rcp_f32_e32 v89, v89
	v_rcp_f32_e32 v180, v180
	v_rcp_f32_e32 v181, v181
	v_mul_f32_e32 v88, v88, v178
	v_mul_f32_e32 v89, v89, v163
	v_mul_f32_e32 v180, v180, v179
	v_mul_f32_e32 v181, v181, v167
	v_mul_f32_e32 v88, v88, v180
	v_mul_f32_e32 v89, v89, v181
	v_lshlrev_b32_e32 v178, 16, v164
	v_and_b32_e32 v164, 0xffff0000, v164
	v_lshlrev_b32_e32 v179, 16, v168
	v_and_b32_e32 v168, 0xffff0000, v168
	v_mul_f32_e32 v82, 0xbfb8aa3b, v82
	v_mul_f32_e32 v83, 0xbfb8aa3b, v83
	v_mul_f32_e32 v180, 0xbfb8aa3b, v179
	v_mul_f32_e32 v181, 0xbfb8aa3b, v168
	v_exp_f32_e32 v82, v82
	v_exp_f32_e32 v83, v83
	v_exp_f32_e32 v180, v180
	v_exp_f32_e32 v181, v181
	v_add_f32_e32 v82, 1.0, v82
	v_add_f32_e32 v83, 1.0, v83
	v_add_f32_e32 v180, 1.0, v180
	v_add_f32_e32 v181, 1.0, v181
	v_rcp_f32_e32 v82, v82
	v_rcp_f32_e32 v83, v83
	v_rcp_f32_e32 v180, v180
	v_rcp_f32_e32 v181, v181
	v_mul_f32_e32 v82, v82, v178
	v_mul_f32_e32 v83, v83, v164
	v_mul_f32_e32 v180, v180, v179
	v_mul_f32_e32 v181, v181, v168
	v_mul_f32_e32 v82, v82, v180
	v_mul_f32_e32 v83, v83, v181
	v_lshlrev_b32_e32 v178, 16, v165
	v_and_b32_e32 v165, 0xffff0000, v165
	v_lshlrev_b32_e32 v179, 16, v169
	v_and_b32_e32 v169, 0xffff0000, v169
	v_mul_f32_e32 v84, 0xbfb8aa3b, v84
	v_mul_f32_e32 v85, 0xbfb8aa3b, v85
	v_mul_f32_e32 v180, 0xbfb8aa3b, v179
	v_mul_f32_e32 v181, 0xbfb8aa3b, v169
	v_exp_f32_e32 v84, v84
	v_exp_f32_e32 v85, v85
	v_exp_f32_e32 v180, v180
	v_exp_f32_e32 v181, v181
	v_add_f32_e32 v84, 1.0, v84
	v_add_f32_e32 v85, 1.0, v85
	v_add_f32_e32 v180, 1.0, v180
	v_add_f32_e32 v181, 1.0, v181
	v_rcp_f32_e32 v84, v84
	v_rcp_f32_e32 v85, v85
	v_rcp_f32_e32 v180, v180
	v_rcp_f32_e32 v181, v181
	v_mul_f32_e32 v84, v84, v178
	v_mul_f32_e32 v85, v85, v165
	v_mul_f32_e32 v180, v180, v179
	v_mul_f32_e32 v181, v181, v169
	v_mul_f32_e32 v84, v84, v180
	v_mul_f32_e32 v85, v85, v181
	v_cvt_pk_bf16_f32 v86, v86, v87
	v_cvt_pk_bf16_f32 v87, v88, v89
	v_cvt_pk_bf16_f32 v88, v82, v83
	v_cvt_pk_bf16_f32 v89, v84, v85
	global_store_dwordx4 v[146:147], v[86:89], off offset:256
	s_mov_b64 s[58:59], 0x20000
	v_lshl_add_u64 v[146:147], v[146:147], 0, s[58:59]
	s_mov_b64 s[58:59], 0x28000
	v_lshl_add_u64 v[142:143], v[142:143], 0, s[58:59]
	s_mov_b64 s[58:59], 0x14000
	v_lshl_add_u64 v[144:145], v[144:145], 0, s[58:59]
	global_load_dwordx4 v[162:165], v[142:143], off
	global_load_dwordx4 v[166:169], v[144:145], off
	s_waitcnt vmcnt(6)
	v_lshlrev_b32_e32 v178, 16, v170
	v_and_b32_e32 v170, 0xffff0000, v170
	v_lshlrev_b32_e32 v179, 16, v174
	v_and_b32_e32 v174, 0xffff0000, v174
	v_mul_f32_e32 v78, 0xbfb8aa3b, v78
	v_mul_f32_e32 v79, 0xbfb8aa3b, v79
	v_mul_f32_e32 v180, 0xbfb8aa3b, v179
	v_mul_f32_e32 v181, 0xbfb8aa3b, v174
	v_exp_f32_e32 v78, v78
	v_exp_f32_e32 v79, v79
	v_exp_f32_e32 v180, v180
	v_exp_f32_e32 v181, v181
	v_add_f32_e32 v78, 1.0, v78
	v_add_f32_e32 v79, 1.0, v79
	v_add_f32_e32 v180, 1.0, v180
	v_add_f32_e32 v181, 1.0, v181
	v_rcp_f32_e32 v78, v78
	v_rcp_f32_e32 v79, v79
	v_rcp_f32_e32 v180, v180
	v_rcp_f32_e32 v181, v181
	v_mul_f32_e32 v78, v78, v178
	v_mul_f32_e32 v79, v79, v170
	v_mul_f32_e32 v180, v180, v179
	v_mul_f32_e32 v181, v181, v174
	v_mul_f32_e32 v78, v78, v180
	v_mul_f32_e32 v79, v79, v181
	v_lshlrev_b32_e32 v178, 16, v171
	v_and_b32_e32 v171, 0xffff0000, v171
	v_lshlrev_b32_e32 v179, 16, v175
	v_and_b32_e32 v175, 0xffff0000, v175
	v_mul_f32_e32 v80, 0xbfb8aa3b, v80
	v_mul_f32_e32 v81, 0xbfb8aa3b, v81
	v_mul_f32_e32 v180, 0xbfb8aa3b, v179
	v_mul_f32_e32 v181, 0xbfb8aa3b, v175
	v_exp_f32_e32 v80, v80
	v_exp_f32_e32 v81, v81
	v_exp_f32_e32 v180, v180
	v_exp_f32_e32 v181, v181
	v_add_f32_e32 v80, 1.0, v80
	v_add_f32_e32 v81, 1.0, v81
	v_add_f32_e32 v180, 1.0, v180
	v_add_f32_e32 v181, 1.0, v181
	v_rcp_f32_e32 v80, v80
	v_rcp_f32_e32 v81, v81
	v_rcp_f32_e32 v180, v180
	v_rcp_f32_e32 v181, v181
	v_mul_f32_e32 v80, v80, v178
	v_mul_f32_e32 v81, v81, v171
	v_mul_f32_e32 v180, v180, v179
	v_mul_f32_e32 v181, v181, v175
	v_mul_f32_e32 v80, v80, v180
	v_mul_f32_e32 v81, v81, v181
	v_lshlrev_b32_e32 v178, 16, v172
	v_and_b32_e32 v172, 0xffff0000, v172
	v_lshlrev_b32_e32 v179, 16, v176
	v_and_b32_e32 v176, 0xffff0000, v176
	v_mul_f32_e32 v74, 0xbfb8aa3b, v74
	v_mul_f32_e32 v75, 0xbfb8aa3b, v75
	v_mul_f32_e32 v180, 0xbfb8aa3b, v179
	v_mul_f32_e32 v181, 0xbfb8aa3b, v176
	v_exp_f32_e32 v74, v74
	v_exp_f32_e32 v75, v75
	v_exp_f32_e32 v180, v180
	v_exp_f32_e32 v181, v181
	v_add_f32_e32 v74, 1.0, v74
	v_add_f32_e32 v75, 1.0, v75
	v_add_f32_e32 v180, 1.0, v180
	v_add_f32_e32 v181, 1.0, v181
	v_rcp_f32_e32 v74, v74
	v_rcp_f32_e32 v75, v75
	v_rcp_f32_e32 v180, v180
	v_rcp_f32_e32 v181, v181
	v_mul_f32_e32 v74, v74, v178
	v_mul_f32_e32 v75, v75, v172
	v_mul_f32_e32 v180, v180, v179
	v_mul_f32_e32 v181, v181, v176
	v_mul_f32_e32 v74, v74, v180
	v_mul_f32_e32 v75, v75, v181
	v_lshlrev_b32_e32 v178, 16, v173
	v_and_b32_e32 v173, 0xffff0000, v173
	v_lshlrev_b32_e32 v179, 16, v177
	v_and_b32_e32 v177, 0xffff0000, v177
	v_mul_f32_e32 v76, 0xbfb8aa3b, v76
	v_mul_f32_e32 v77, 0xbfb8aa3b, v77
	v_mul_f32_e32 v180, 0xbfb8aa3b, v179
	v_mul_f32_e32 v181, 0xbfb8aa3b, v177
	v_exp_f32_e32 v76, v76
	v_exp_f32_e32 v77, v77
	v_exp_f32_e32 v180, v180
	v_exp_f32_e32 v181, v181
	v_add_f32_e32 v76, 1.0, v76
	v_add_f32_e32 v77, 1.0, v77
	v_add_f32_e32 v180, 1.0, v180
	v_add_f32_e32 v181, 1.0, v181
	v_rcp_f32_e32 v76, v76
	v_rcp_f32_e32 v77, v77
	v_rcp_f32_e32 v180, v180
	v_rcp_f32_e32 v181, v181
	v_mul_f32_e32 v76, v76, v178
	v_mul_f32_e32 v77, v77, v173
	v_mul_f32_e32 v180, v180, v179
	v_mul_f32_e32 v181, v181, v177
	v_mul_f32_e32 v76, v76, v180
	v_mul_f32_e32 v77, v77, v181
	v_cvt_pk_bf16_f32 v78, v78, v79
	v_cvt_pk_bf16_f32 v79, v80, v81
	v_cvt_pk_bf16_f32 v80, v74, v75
	v_cvt_pk_bf16_f32 v81, v76, v77
	global_store_dwordx4 v[146:147], v[78:81], off
	global_load_dwordx4 v[170:173], v[142:143], off offset:256
	global_load_dwordx4 v[174:177], v[144:145], off offset:256
	s_waitcnt vmcnt(6)
	v_lshlrev_b32_e32 v178, 16, v154
	v_and_b32_e32 v154, 0xffff0000, v154
	v_lshlrev_b32_e32 v179, 16, v158
	v_and_b32_e32 v158, 0xffff0000, v158
	v_mul_f32_e32 v70, 0xbfb8aa3b, v70
	v_mul_f32_e32 v71, 0xbfb8aa3b, v71
	v_mul_f32_e32 v180, 0xbfb8aa3b, v179
	v_mul_f32_e32 v181, 0xbfb8aa3b, v158
	v_exp_f32_e32 v70, v70
	v_exp_f32_e32 v71, v71
	v_exp_f32_e32 v180, v180
	v_exp_f32_e32 v181, v181
	v_add_f32_e32 v70, 1.0, v70
	v_add_f32_e32 v71, 1.0, v71
	v_add_f32_e32 v180, 1.0, v180
	v_add_f32_e32 v181, 1.0, v181
	v_rcp_f32_e32 v70, v70
	v_rcp_f32_e32 v71, v71
	v_rcp_f32_e32 v180, v180
	v_rcp_f32_e32 v181, v181
	v_mul_f32_e32 v70, v70, v178
	v_mul_f32_e32 v71, v71, v154
	v_mul_f32_e32 v180, v180, v179
	v_mul_f32_e32 v181, v181, v158
	v_mul_f32_e32 v70, v70, v180
	v_mul_f32_e32 v71, v71, v181
	v_lshlrev_b32_e32 v178, 16, v155
	v_and_b32_e32 v155, 0xffff0000, v155
	v_lshlrev_b32_e32 v179, 16, v159
	v_and_b32_e32 v159, 0xffff0000, v159
	v_mul_f32_e32 v72, 0xbfb8aa3b, v72
	v_mul_f32_e32 v73, 0xbfb8aa3b, v73
	v_mul_f32_e32 v180, 0xbfb8aa3b, v179
	v_mul_f32_e32 v181, 0xbfb8aa3b, v159
	v_exp_f32_e32 v72, v72
	v_exp_f32_e32 v73, v73
	v_exp_f32_e32 v180, v180
	v_exp_f32_e32 v181, v181
	v_add_f32_e32 v72, 1.0, v72
	v_add_f32_e32 v73, 1.0, v73
	v_add_f32_e32 v180, 1.0, v180
	v_add_f32_e32 v181, 1.0, v181
	v_rcp_f32_e32 v72, v72
	v_rcp_f32_e32 v73, v73
	v_rcp_f32_e32 v180, v180
	v_rcp_f32_e32 v181, v181
	v_mul_f32_e32 v72, v72, v178
	v_mul_f32_e32 v73, v73, v155
	v_mul_f32_e32 v180, v180, v179
	v_mul_f32_e32 v181, v181, v159
	v_mul_f32_e32 v72, v72, v180
	v_mul_f32_e32 v73, v73, v181
	v_lshlrev_b32_e32 v178, 16, v156
	v_and_b32_e32 v156, 0xffff0000, v156
	v_lshlrev_b32_e32 v179, 16, v160
	v_and_b32_e32 v160, 0xffff0000, v160
	v_mul_f32_e32 v66, 0xbfb8aa3b, v66
	v_mul_f32_e32 v67, 0xbfb8aa3b, v67
	v_mul_f32_e32 v180, 0xbfb8aa3b, v179
	v_mul_f32_e32 v181, 0xbfb8aa3b, v160
	v_exp_f32_e32 v66, v66
	v_exp_f32_e32 v67, v67
	v_exp_f32_e32 v180, v180
	v_exp_f32_e32 v181, v181
	v_add_f32_e32 v66, 1.0, v66
	v_add_f32_e32 v67, 1.0, v67
	v_add_f32_e32 v180, 1.0, v180
	v_add_f32_e32 v181, 1.0, v181
	v_rcp_f32_e32 v66, v66
	v_rcp_f32_e32 v67, v67
	v_rcp_f32_e32 v180, v180
	v_rcp_f32_e32 v181, v181
	v_mul_f32_e32 v66, v66, v178
	v_mul_f32_e32 v67, v67, v156
	v_mul_f32_e32 v180, v180, v179
	v_mul_f32_e32 v181, v181, v160
	v_mul_f32_e32 v66, v66, v180
	v_mul_f32_e32 v67, v67, v181
	v_lshlrev_b32_e32 v178, 16, v157
	v_and_b32_e32 v157, 0xffff0000, v157
	v_lshlrev_b32_e32 v179, 16, v161
	v_and_b32_e32 v161, 0xffff0000, v161
	v_mul_f32_e32 v68, 0xbfb8aa3b, v68
	v_mul_f32_e32 v69, 0xbfb8aa3b, v69
	v_mul_f32_e32 v180, 0xbfb8aa3b, v179
	v_mul_f32_e32 v181, 0xbfb8aa3b, v161
	v_exp_f32_e32 v68, v68
	v_exp_f32_e32 v69, v69
	v_exp_f32_e32 v180, v180
	v_exp_f32_e32 v181, v181
	v_add_f32_e32 v68, 1.0, v68
	v_add_f32_e32 v69, 1.0, v69
	v_add_f32_e32 v180, 1.0, v180
	v_add_f32_e32 v181, 1.0, v181
	v_rcp_f32_e32 v68, v68
	v_rcp_f32_e32 v69, v69
	v_rcp_f32_e32 v180, v180
	v_rcp_f32_e32 v181, v181
	v_mul_f32_e32 v68, v68, v178
	v_mul_f32_e32 v69, v69, v157
	v_mul_f32_e32 v180, v180, v179
	v_mul_f32_e32 v181, v181, v161
	v_mul_f32_e32 v68, v68, v180
	v_mul_f32_e32 v69, v69, v181
	v_cvt_pk_bf16_f32 v70, v70, v71
	v_cvt_pk_bf16_f32 v71, v72, v73
	v_cvt_pk_bf16_f32 v72, v66, v67
	v_cvt_pk_bf16_f32 v73, v68, v69
	global_store_dwordx4 v[146:147], v[70:73], off offset:256
	s_mov_b64 s[58:59], 0xa0000
	v_lshl_add_u64 v[146:147], v[146:147], 0, s[58:59]
	s_mov_b64 s[58:59], 0x8000
	v_lshl_add_u64 v[142:143], v[142:143], 0, s[58:59]
	s_mov_b64 s[58:59], 0x4000
	v_lshl_add_u64 v[144:145], v[144:145], 0, s[58:59]
	global_load_dwordx4 v[154:157], v[142:143], off
	global_load_dwordx4 v[158:161], v[144:145], off
	s_waitcnt vmcnt(6)
	v_lshlrev_b32_e32 v178, 16, v162
	v_and_b32_e32 v162, 0xffff0000, v162
	v_lshlrev_b32_e32 v179, 16, v166
	v_and_b32_e32 v166, 0xffff0000, v166
	v_mul_f32_e32 v62, 0xbfb8aa3b, v62
	v_mul_f32_e32 v63, 0xbfb8aa3b, v63
	v_mul_f32_e32 v180, 0xbfb8aa3b, v179
	v_mul_f32_e32 v181, 0xbfb8aa3b, v166
	v_exp_f32_e32 v62, v62
	v_exp_f32_e32 v63, v63
	v_exp_f32_e32 v180, v180
	v_exp_f32_e32 v181, v181
	v_add_f32_e32 v62, 1.0, v62
	v_add_f32_e32 v63, 1.0, v63
	v_add_f32_e32 v180, 1.0, v180
	v_add_f32_e32 v181, 1.0, v181
	v_rcp_f32_e32 v62, v62
	v_rcp_f32_e32 v63, v63
	v_rcp_f32_e32 v180, v180
	v_rcp_f32_e32 v181, v181
	v_mul_f32_e32 v62, v62, v178
	v_mul_f32_e32 v63, v63, v162
	v_mul_f32_e32 v180, v180, v179
	v_mul_f32_e32 v181, v181, v166
	v_mul_f32_e32 v62, v62, v180
	v_mul_f32_e32 v63, v63, v181
	v_lshlrev_b32_e32 v178, 16, v163
	v_and_b32_e32 v163, 0xffff0000, v163
	v_lshlrev_b32_e32 v179, 16, v167
	v_and_b32_e32 v167, 0xffff0000, v167
	v_mul_f32_e32 v64, 0xbfb8aa3b, v64
	v_mul_f32_e32 v65, 0xbfb8aa3b, v65
	v_mul_f32_e32 v180, 0xbfb8aa3b, v179
	v_mul_f32_e32 v181, 0xbfb8aa3b, v167
	v_exp_f32_e32 v64, v64
	v_exp_f32_e32 v65, v65
	v_exp_f32_e32 v180, v180
	v_exp_f32_e32 v181, v181
	v_add_f32_e32 v64, 1.0, v64
	v_add_f32_e32 v65, 1.0, v65
	v_add_f32_e32 v180, 1.0, v180
	v_add_f32_e32 v181, 1.0, v181
	v_rcp_f32_e32 v64, v64
	v_rcp_f32_e32 v65, v65
	v_rcp_f32_e32 v180, v180
	v_rcp_f32_e32 v181, v181
	v_mul_f32_e32 v64, v64, v178
	v_mul_f32_e32 v65, v65, v163
	v_mul_f32_e32 v180, v180, v179
	v_mul_f32_e32 v181, v181, v167
	v_mul_f32_e32 v64, v64, v180
	v_mul_f32_e32 v65, v65, v181
	v_lshlrev_b32_e32 v178, 16, v164
	v_and_b32_e32 v164, 0xffff0000, v164
	v_lshlrev_b32_e32 v179, 16, v168
	v_and_b32_e32 v168, 0xffff0000, v168
	v_mul_f32_e32 v58, 0xbfb8aa3b, v58
	v_mul_f32_e32 v59, 0xbfb8aa3b, v59
	v_mul_f32_e32 v180, 0xbfb8aa3b, v179
	v_mul_f32_e32 v181, 0xbfb8aa3b, v168
	v_exp_f32_e32 v58, v58
	v_exp_f32_e32 v59, v59
	v_exp_f32_e32 v180, v180
	v_exp_f32_e32 v181, v181
	v_add_f32_e32 v58, 1.0, v58
	v_add_f32_e32 v59, 1.0, v59
	v_add_f32_e32 v180, 1.0, v180
	v_add_f32_e32 v181, 1.0, v181
	v_rcp_f32_e32 v58, v58
	v_rcp_f32_e32 v59, v59
	v_rcp_f32_e32 v180, v180
	v_rcp_f32_e32 v181, v181
	v_mul_f32_e32 v58, v58, v178
	v_mul_f32_e32 v59, v59, v164
	v_mul_f32_e32 v180, v180, v179
	v_mul_f32_e32 v181, v181, v168
	v_mul_f32_e32 v58, v58, v180
	v_mul_f32_e32 v59, v59, v181
	v_lshlrev_b32_e32 v178, 16, v165
	v_and_b32_e32 v165, 0xffff0000, v165
	v_lshlrev_b32_e32 v179, 16, v169
	v_and_b32_e32 v169, 0xffff0000, v169
	v_mul_f32_e32 v60, 0xbfb8aa3b, v60
	v_mul_f32_e32 v61, 0xbfb8aa3b, v61
	v_mul_f32_e32 v180, 0xbfb8aa3b, v179
	v_mul_f32_e32 v181, 0xbfb8aa3b, v169
	v_exp_f32_e32 v60, v60
	v_exp_f32_e32 v61, v61
	v_exp_f32_e32 v180, v180
	v_exp_f32_e32 v181, v181
	v_add_f32_e32 v60, 1.0, v60
	v_add_f32_e32 v61, 1.0, v61
	v_add_f32_e32 v180, 1.0, v180
	v_add_f32_e32 v181, 1.0, v181
	v_rcp_f32_e32 v60, v60
	v_rcp_f32_e32 v61, v61
	v_rcp_f32_e32 v180, v180
	v_rcp_f32_e32 v181, v181
	v_mul_f32_e32 v60, v60, v178
	v_mul_f32_e32 v61, v61, v165
	v_mul_f32_e32 v180, v180, v179
	v_mul_f32_e32 v181, v181, v169
	v_mul_f32_e32 v60, v60, v180
	v_mul_f32_e32 v61, v61, v181
	v_cvt_pk_bf16_f32 v62, v62, v63
	v_cvt_pk_bf16_f32 v63, v64, v65
	v_cvt_pk_bf16_f32 v64, v58, v59
	v_cvt_pk_bf16_f32 v65, v60, v61
	global_store_dwordx4 v[146:147], v[62:65], off
	global_load_dwordx4 v[162:165], v[142:143], off offset:256
	global_load_dwordx4 v[166:169], v[144:145], off offset:256
	s_waitcnt vmcnt(6)
	v_lshlrev_b32_e32 v178, 16, v170
	v_and_b32_e32 v170, 0xffff0000, v170
	v_lshlrev_b32_e32 v179, 16, v174
	v_and_b32_e32 v174, 0xffff0000, v174
	v_mul_f32_e32 v54, 0xbfb8aa3b, v54
	v_mul_f32_e32 v55, 0xbfb8aa3b, v55
	v_mul_f32_e32 v180, 0xbfb8aa3b, v179
	v_mul_f32_e32 v181, 0xbfb8aa3b, v174
	v_exp_f32_e32 v54, v54
	v_exp_f32_e32 v55, v55
	v_exp_f32_e32 v180, v180
	v_exp_f32_e32 v181, v181
	v_add_f32_e32 v54, 1.0, v54
	v_add_f32_e32 v55, 1.0, v55
	v_add_f32_e32 v180, 1.0, v180
	v_add_f32_e32 v181, 1.0, v181
	v_rcp_f32_e32 v54, v54
	v_rcp_f32_e32 v55, v55
	v_rcp_f32_e32 v180, v180
	v_rcp_f32_e32 v181, v181
	v_mul_f32_e32 v54, v54, v178
	v_mul_f32_e32 v55, v55, v170
	v_mul_f32_e32 v180, v180, v179
	v_mul_f32_e32 v181, v181, v174
	v_mul_f32_e32 v54, v54, v180
	v_mul_f32_e32 v55, v55, v181
	v_lshlrev_b32_e32 v178, 16, v171
	v_and_b32_e32 v171, 0xffff0000, v171
	v_lshlrev_b32_e32 v179, 16, v175
	v_and_b32_e32 v175, 0xffff0000, v175
	v_mul_f32_e32 v56, 0xbfb8aa3b, v56
	v_mul_f32_e32 v57, 0xbfb8aa3b, v57
	v_mul_f32_e32 v180, 0xbfb8aa3b, v179
	v_mul_f32_e32 v181, 0xbfb8aa3b, v175
	v_exp_f32_e32 v56, v56
	v_exp_f32_e32 v57, v57
	v_exp_f32_e32 v180, v180
	v_exp_f32_e32 v181, v181
	v_add_f32_e32 v56, 1.0, v56
	v_add_f32_e32 v57, 1.0, v57
	v_add_f32_e32 v180, 1.0, v180
	v_add_f32_e32 v181, 1.0, v181
	v_rcp_f32_e32 v56, v56
	v_rcp_f32_e32 v57, v57
	v_rcp_f32_e32 v180, v180
	v_rcp_f32_e32 v181, v181
	v_mul_f32_e32 v56, v56, v178
	v_mul_f32_e32 v57, v57, v171
	v_mul_f32_e32 v180, v180, v179
	v_mul_f32_e32 v181, v181, v175
	v_mul_f32_e32 v56, v56, v180
	v_mul_f32_e32 v57, v57, v181
	v_lshlrev_b32_e32 v178, 16, v172
	v_and_b32_e32 v172, 0xffff0000, v172
	v_lshlrev_b32_e32 v179, 16, v176
	v_and_b32_e32 v176, 0xffff0000, v176
	v_mul_f32_e32 v50, 0xbfb8aa3b, v50
	v_mul_f32_e32 v51, 0xbfb8aa3b, v51
	v_mul_f32_e32 v180, 0xbfb8aa3b, v179
	v_mul_f32_e32 v181, 0xbfb8aa3b, v176
	v_exp_f32_e32 v50, v50
	v_exp_f32_e32 v51, v51
	v_exp_f32_e32 v180, v180
	v_exp_f32_e32 v181, v181
	v_add_f32_e32 v50, 1.0, v50
	v_add_f32_e32 v51, 1.0, v51
	v_add_f32_e32 v180, 1.0, v180
	v_add_f32_e32 v181, 1.0, v181
	v_rcp_f32_e32 v50, v50
	v_rcp_f32_e32 v51, v51
	v_rcp_f32_e32 v180, v180
	v_rcp_f32_e32 v181, v181
	v_mul_f32_e32 v50, v50, v178
	v_mul_f32_e32 v51, v51, v172
	v_mul_f32_e32 v180, v180, v179
	v_mul_f32_e32 v181, v181, v176
	v_mul_f32_e32 v50, v50, v180
	v_mul_f32_e32 v51, v51, v181
	v_lshlrev_b32_e32 v178, 16, v173
	v_and_b32_e32 v173, 0xffff0000, v173
	v_lshlrev_b32_e32 v179, 16, v177
	v_and_b32_e32 v177, 0xffff0000, v177
	v_mul_f32_e32 v52, 0xbfb8aa3b, v52
	v_mul_f32_e32 v53, 0xbfb8aa3b, v53
	v_mul_f32_e32 v180, 0xbfb8aa3b, v179
	v_mul_f32_e32 v181, 0xbfb8aa3b, v177
	v_exp_f32_e32 v52, v52
	v_exp_f32_e32 v53, v53
	v_exp_f32_e32 v180, v180
	v_exp_f32_e32 v181, v181
	v_add_f32_e32 v52, 1.0, v52
	v_add_f32_e32 v53, 1.0, v53
	v_add_f32_e32 v180, 1.0, v180
	v_add_f32_e32 v181, 1.0, v181
	v_rcp_f32_e32 v52, v52
	v_rcp_f32_e32 v53, v53
	v_rcp_f32_e32 v180, v180
	v_rcp_f32_e32 v181, v181
	v_mul_f32_e32 v52, v52, v178
	v_mul_f32_e32 v53, v53, v173
	v_mul_f32_e32 v180, v180, v179
	v_mul_f32_e32 v181, v181, v177
	v_mul_f32_e32 v52, v52, v180
	v_mul_f32_e32 v53, v53, v181
	v_cvt_pk_bf16_f32 v54, v54, v55
	v_cvt_pk_bf16_f32 v55, v56, v57
	v_cvt_pk_bf16_f32 v56, v50, v51
	v_cvt_pk_bf16_f32 v57, v52, v53
	global_store_dwordx4 v[146:147], v[54:57], off offset:256
	s_mov_b64 s[58:59], 0x20000
	v_lshl_add_u64 v[146:147], v[146:147], 0, s[58:59]
	s_mov_b64 s[58:59], 0x8000
	v_lshl_add_u64 v[142:143], v[142:143], 0, s[58:59]
	s_mov_b64 s[58:59], 0x4000
	v_lshl_add_u64 v[144:145], v[144:145], 0, s[58:59]
	global_load_dwordx4 v[170:173], v[142:143], off
	global_load_dwordx4 v[174:177], v[144:145], off
	s_waitcnt vmcnt(6)
	v_lshlrev_b32_e32 v178, 16, v154
	v_and_b32_e32 v154, 0xffff0000, v154
	v_lshlrev_b32_e32 v179, 16, v158
	v_and_b32_e32 v158, 0xffff0000, v158
	v_mul_f32_e32 v46, 0xbfb8aa3b, v46
	v_mul_f32_e32 v47, 0xbfb8aa3b, v47
	v_mul_f32_e32 v180, 0xbfb8aa3b, v179
	v_mul_f32_e32 v181, 0xbfb8aa3b, v158
	v_exp_f32_e32 v46, v46
	v_exp_f32_e32 v47, v47
	v_exp_f32_e32 v180, v180
	v_exp_f32_e32 v181, v181
	v_add_f32_e32 v46, 1.0, v46
	v_add_f32_e32 v47, 1.0, v47
	v_add_f32_e32 v180, 1.0, v180
	v_add_f32_e32 v181, 1.0, v181
	v_rcp_f32_e32 v46, v46
	v_rcp_f32_e32 v47, v47
	v_rcp_f32_e32 v180, v180
	v_rcp_f32_e32 v181, v181
	v_mul_f32_e32 v46, v46, v178
	v_mul_f32_e32 v47, v47, v154
	v_mul_f32_e32 v180, v180, v179
	v_mul_f32_e32 v181, v181, v158
	v_mul_f32_e32 v46, v46, v180
	v_mul_f32_e32 v47, v47, v181
	v_lshlrev_b32_e32 v178, 16, v155
	v_and_b32_e32 v155, 0xffff0000, v155
	v_lshlrev_b32_e32 v179, 16, v159
	v_and_b32_e32 v159, 0xffff0000, v159
	v_mul_f32_e32 v48, 0xbfb8aa3b, v48
	v_mul_f32_e32 v49, 0xbfb8aa3b, v49
	v_mul_f32_e32 v180, 0xbfb8aa3b, v179
	v_mul_f32_e32 v181, 0xbfb8aa3b, v159
	v_exp_f32_e32 v48, v48
	v_exp_f32_e32 v49, v49
	v_exp_f32_e32 v180, v180
	v_exp_f32_e32 v181, v181
	v_add_f32_e32 v48, 1.0, v48
	v_add_f32_e32 v49, 1.0, v49
	v_add_f32_e32 v180, 1.0, v180
	v_add_f32_e32 v181, 1.0, v181
	v_rcp_f32_e32 v48, v48
	v_rcp_f32_e32 v49, v49
	v_rcp_f32_e32 v180, v180
	v_rcp_f32_e32 v181, v181
	v_mul_f32_e32 v48, v48, v178
	v_mul_f32_e32 v49, v49, v155
	v_mul_f32_e32 v180, v180, v179
	v_mul_f32_e32 v181, v181, v159
	v_mul_f32_e32 v48, v48, v180
	v_mul_f32_e32 v49, v49, v181
	v_lshlrev_b32_e32 v178, 16, v156
	v_and_b32_e32 v156, 0xffff0000, v156
	v_lshlrev_b32_e32 v179, 16, v160
	v_and_b32_e32 v160, 0xffff0000, v160
	v_mul_f32_e32 v42, 0xbfb8aa3b, v42
	v_mul_f32_e32 v43, 0xbfb8aa3b, v43
	v_mul_f32_e32 v180, 0xbfb8aa3b, v179
	v_mul_f32_e32 v181, 0xbfb8aa3b, v160
	v_exp_f32_e32 v42, v42
	v_exp_f32_e32 v43, v43
	v_exp_f32_e32 v180, v180
	v_exp_f32_e32 v181, v181
	v_add_f32_e32 v42, 1.0, v42
	v_add_f32_e32 v43, 1.0, v43
	v_add_f32_e32 v180, 1.0, v180
	v_add_f32_e32 v181, 1.0, v181
	v_rcp_f32_e32 v42, v42
	v_rcp_f32_e32 v43, v43
	v_rcp_f32_e32 v180, v180
	v_rcp_f32_e32 v181, v181
	v_mul_f32_e32 v42, v42, v178
	v_mul_f32_e32 v43, v43, v156
	v_mul_f32_e32 v180, v180, v179
	v_mul_f32_e32 v181, v181, v160
	v_mul_f32_e32 v42, v42, v180
	v_mul_f32_e32 v43, v43, v181
	v_lshlrev_b32_e32 v178, 16, v157
	v_and_b32_e32 v157, 0xffff0000, v157
	v_lshlrev_b32_e32 v179, 16, v161
	v_and_b32_e32 v161, 0xffff0000, v161
	v_mul_f32_e32 v44, 0xbfb8aa3b, v44
	v_mul_f32_e32 v45, 0xbfb8aa3b, v45
	v_mul_f32_e32 v180, 0xbfb8aa3b, v179
	v_mul_f32_e32 v181, 0xbfb8aa3b, v161
	v_exp_f32_e32 v44, v44
	v_exp_f32_e32 v45, v45
	v_exp_f32_e32 v180, v180
	v_exp_f32_e32 v181, v181
	v_add_f32_e32 v44, 1.0, v44
	v_add_f32_e32 v45, 1.0, v45
	v_add_f32_e32 v180, 1.0, v180
	v_add_f32_e32 v181, 1.0, v181
	v_rcp_f32_e32 v44, v44
	v_rcp_f32_e32 v45, v45
	v_rcp_f32_e32 v180, v180
	v_rcp_f32_e32 v181, v181
	v_mul_f32_e32 v44, v44, v178
	v_mul_f32_e32 v45, v45, v157
	v_mul_f32_e32 v180, v180, v179
	v_mul_f32_e32 v181, v181, v161
	v_mul_f32_e32 v44, v44, v180
	v_mul_f32_e32 v45, v45, v181
	v_cvt_pk_bf16_f32 v46, v46, v47
	v_cvt_pk_bf16_f32 v47, v48, v49
	v_cvt_pk_bf16_f32 v48, v42, v43
	v_cvt_pk_bf16_f32 v49, v44, v45
	global_store_dwordx4 v[146:147], v[46:49], off
	global_load_dwordx4 v[154:157], v[142:143], off offset:256
	global_load_dwordx4 v[158:161], v[144:145], off offset:256
	s_waitcnt vmcnt(6)
	v_lshlrev_b32_e32 v178, 16, v162
	v_and_b32_e32 v162, 0xffff0000, v162
	v_lshlrev_b32_e32 v179, 16, v166
	v_and_b32_e32 v166, 0xffff0000, v166
	v_mul_f32_e32 v38, 0xbfb8aa3b, v38
	v_mul_f32_e32 v39, 0xbfb8aa3b, v39
	v_mul_f32_e32 v180, 0xbfb8aa3b, v179
	v_mul_f32_e32 v181, 0xbfb8aa3b, v166
	v_exp_f32_e32 v38, v38
	v_exp_f32_e32 v39, v39
	v_exp_f32_e32 v180, v180
	v_exp_f32_e32 v181, v181
	v_add_f32_e32 v38, 1.0, v38
	v_add_f32_e32 v39, 1.0, v39
	v_add_f32_e32 v180, 1.0, v180
	v_add_f32_e32 v181, 1.0, v181
	v_rcp_f32_e32 v38, v38
	v_rcp_f32_e32 v39, v39
	v_rcp_f32_e32 v180, v180
	v_rcp_f32_e32 v181, v181
	v_mul_f32_e32 v38, v38, v178
	v_mul_f32_e32 v39, v39, v162
	v_mul_f32_e32 v180, v180, v179
	v_mul_f32_e32 v181, v181, v166
	v_mul_f32_e32 v38, v38, v180
	v_mul_f32_e32 v39, v39, v181
	v_lshlrev_b32_e32 v178, 16, v163
	v_and_b32_e32 v163, 0xffff0000, v163
	v_lshlrev_b32_e32 v179, 16, v167
	v_and_b32_e32 v167, 0xffff0000, v167
	v_mul_f32_e32 v40, 0xbfb8aa3b, v40
	v_mul_f32_e32 v41, 0xbfb8aa3b, v41
	v_mul_f32_e32 v180, 0xbfb8aa3b, v179
	v_mul_f32_e32 v181, 0xbfb8aa3b, v167
	v_exp_f32_e32 v40, v40
	v_exp_f32_e32 v41, v41
	v_exp_f32_e32 v180, v180
	v_exp_f32_e32 v181, v181
	v_add_f32_e32 v40, 1.0, v40
	v_add_f32_e32 v41, 1.0, v41
	v_add_f32_e32 v180, 1.0, v180
	v_add_f32_e32 v181, 1.0, v181
	v_rcp_f32_e32 v40, v40
	v_rcp_f32_e32 v41, v41
	v_rcp_f32_e32 v180, v180
	v_rcp_f32_e32 v181, v181
	v_mul_f32_e32 v40, v40, v178
	v_mul_f32_e32 v41, v41, v163
	v_mul_f32_e32 v180, v180, v179
	v_mul_f32_e32 v181, v181, v167
	v_mul_f32_e32 v40, v40, v180
	v_mul_f32_e32 v41, v41, v181
	v_lshlrev_b32_e32 v178, 16, v164
	v_and_b32_e32 v164, 0xffff0000, v164
	v_lshlrev_b32_e32 v179, 16, v168
	v_and_b32_e32 v168, 0xffff0000, v168
	v_mul_f32_e32 v34, 0xbfb8aa3b, v34
	v_mul_f32_e32 v35, 0xbfb8aa3b, v35
	v_mul_f32_e32 v180, 0xbfb8aa3b, v179
	v_mul_f32_e32 v181, 0xbfb8aa3b, v168
	v_exp_f32_e32 v34, v34
	v_exp_f32_e32 v35, v35
	v_exp_f32_e32 v180, v180
	v_exp_f32_e32 v181, v181
	v_add_f32_e32 v34, 1.0, v34
	v_add_f32_e32 v35, 1.0, v35
	v_add_f32_e32 v180, 1.0, v180
	v_add_f32_e32 v181, 1.0, v181
	v_rcp_f32_e32 v34, v34
	v_rcp_f32_e32 v35, v35
	v_rcp_f32_e32 v180, v180
	v_rcp_f32_e32 v181, v181
	v_mul_f32_e32 v34, v34, v178
	v_mul_f32_e32 v35, v35, v164
	v_mul_f32_e32 v180, v180, v179
	v_mul_f32_e32 v181, v181, v168
	v_mul_f32_e32 v34, v34, v180
	v_mul_f32_e32 v35, v35, v181
	v_lshlrev_b32_e32 v178, 16, v165
	v_and_b32_e32 v165, 0xffff0000, v165
	v_lshlrev_b32_e32 v179, 16, v169
	v_and_b32_e32 v169, 0xffff0000, v169
	v_mul_f32_e32 v36, 0xbfb8aa3b, v36
	v_mul_f32_e32 v37, 0xbfb8aa3b, v37
	v_mul_f32_e32 v180, 0xbfb8aa3b, v179
	v_mul_f32_e32 v181, 0xbfb8aa3b, v169
	v_exp_f32_e32 v36, v36
	v_exp_f32_e32 v37, v37
	v_exp_f32_e32 v180, v180
	v_exp_f32_e32 v181, v181
	v_add_f32_e32 v36, 1.0, v36
	v_add_f32_e32 v37, 1.0, v37
	v_add_f32_e32 v180, 1.0, v180
	v_add_f32_e32 v181, 1.0, v181
	v_rcp_f32_e32 v36, v36
	v_rcp_f32_e32 v37, v37
	v_rcp_f32_e32 v180, v180
	v_rcp_f32_e32 v181, v181
	v_mul_f32_e32 v36, v36, v178
	v_mul_f32_e32 v37, v37, v165
	v_mul_f32_e32 v180, v180, v179
	v_mul_f32_e32 v181, v181, v169
	v_mul_f32_e32 v36, v36, v180
	v_mul_f32_e32 v37, v37, v181
	v_cvt_pk_bf16_f32 v38, v38, v39
	v_cvt_pk_bf16_f32 v39, v40, v41
	v_cvt_pk_bf16_f32 v40, v34, v35
	v_cvt_pk_bf16_f32 v41, v36, v37
	global_store_dwordx4 v[146:147], v[38:41], off offset:256
	s_mov_b64 s[58:59], 0x20000
	v_lshl_add_u64 v[146:147], v[146:147], 0, s[58:59]
	s_mov_b64 s[58:59], 0x8000
	v_lshl_add_u64 v[142:143], v[142:143], 0, s[58:59]
	s_mov_b64 s[58:59], 0x4000
	v_lshl_add_u64 v[144:145], v[144:145], 0, s[58:59]
	global_load_dwordx4 v[162:165], v[142:143], off
	global_load_dwordx4 v[166:169], v[144:145], off
	s_waitcnt vmcnt(6)
	v_lshlrev_b32_e32 v178, 16, v170
	v_and_b32_e32 v170, 0xffff0000, v170
	v_lshlrev_b32_e32 v179, 16, v174
	v_and_b32_e32 v174, 0xffff0000, v174
	v_mul_f32_e32 v30, 0xbfb8aa3b, v30
	v_mul_f32_e32 v31, 0xbfb8aa3b, v31
	v_mul_f32_e32 v180, 0xbfb8aa3b, v179
	v_mul_f32_e32 v181, 0xbfb8aa3b, v174
	v_exp_f32_e32 v30, v30
	v_exp_f32_e32 v31, v31
	v_exp_f32_e32 v180, v180
	v_exp_f32_e32 v181, v181
	v_add_f32_e32 v30, 1.0, v30
	v_add_f32_e32 v31, 1.0, v31
	v_add_f32_e32 v180, 1.0, v180
	v_add_f32_e32 v181, 1.0, v181
	v_rcp_f32_e32 v30, v30
	v_rcp_f32_e32 v31, v31
	v_rcp_f32_e32 v180, v180
	v_rcp_f32_e32 v181, v181
	v_mul_f32_e32 v30, v30, v178
	v_mul_f32_e32 v31, v31, v170
	v_mul_f32_e32 v180, v180, v179
	v_mul_f32_e32 v181, v181, v174
	v_mul_f32_e32 v30, v30, v180
	v_mul_f32_e32 v31, v31, v181
	v_lshlrev_b32_e32 v178, 16, v171
	v_and_b32_e32 v171, 0xffff0000, v171
	v_lshlrev_b32_e32 v179, 16, v175
	v_and_b32_e32 v175, 0xffff0000, v175
	v_mul_f32_e32 v32, 0xbfb8aa3b, v32
	v_mul_f32_e32 v33, 0xbfb8aa3b, v33
	v_mul_f32_e32 v180, 0xbfb8aa3b, v179
	v_mul_f32_e32 v181, 0xbfb8aa3b, v175
	v_exp_f32_e32 v32, v32
	v_exp_f32_e32 v33, v33
	v_exp_f32_e32 v180, v180
	v_exp_f32_e32 v181, v181
	v_add_f32_e32 v32, 1.0, v32
	v_add_f32_e32 v33, 1.0, v33
	v_add_f32_e32 v180, 1.0, v180
	v_add_f32_e32 v181, 1.0, v181
	v_rcp_f32_e32 v32, v32
	v_rcp_f32_e32 v33, v33
	v_rcp_f32_e32 v180, v180
	v_rcp_f32_e32 v181, v181
	v_mul_f32_e32 v32, v32, v178
	v_mul_f32_e32 v33, v33, v171
	v_mul_f32_e32 v180, v180, v179
	v_mul_f32_e32 v181, v181, v175
	v_mul_f32_e32 v32, v32, v180
	v_mul_f32_e32 v33, v33, v181
	v_lshlrev_b32_e32 v178, 16, v172
	v_and_b32_e32 v172, 0xffff0000, v172
	v_lshlrev_b32_e32 v179, 16, v176
	v_and_b32_e32 v176, 0xffff0000, v176
	v_mul_f32_e32 v26, 0xbfb8aa3b, v26
	v_mul_f32_e32 v27, 0xbfb8aa3b, v27
	v_mul_f32_e32 v180, 0xbfb8aa3b, v179
	v_mul_f32_e32 v181, 0xbfb8aa3b, v176
	v_exp_f32_e32 v26, v26
	v_exp_f32_e32 v27, v27
	v_exp_f32_e32 v180, v180
	v_exp_f32_e32 v181, v181
	v_add_f32_e32 v26, 1.0, v26
	v_add_f32_e32 v27, 1.0, v27
	v_add_f32_e32 v180, 1.0, v180
	v_add_f32_e32 v181, 1.0, v181
	v_rcp_f32_e32 v26, v26
	v_rcp_f32_e32 v27, v27
	v_rcp_f32_e32 v180, v180
	v_rcp_f32_e32 v181, v181
	v_mul_f32_e32 v26, v26, v178
	v_mul_f32_e32 v27, v27, v172
	v_mul_f32_e32 v180, v180, v179
	v_mul_f32_e32 v181, v181, v176
	v_mul_f32_e32 v26, v26, v180
	v_mul_f32_e32 v27, v27, v181
	v_lshlrev_b32_e32 v178, 16, v173
	v_and_b32_e32 v173, 0xffff0000, v173
	v_lshlrev_b32_e32 v179, 16, v177
	v_and_b32_e32 v177, 0xffff0000, v177
	v_mul_f32_e32 v28, 0xbfb8aa3b, v28
	v_mul_f32_e32 v29, 0xbfb8aa3b, v29
	v_mul_f32_e32 v180, 0xbfb8aa3b, v179
	v_mul_f32_e32 v181, 0xbfb8aa3b, v177
	v_exp_f32_e32 v28, v28
	v_exp_f32_e32 v29, v29
	v_exp_f32_e32 v180, v180
	v_exp_f32_e32 v181, v181
	v_add_f32_e32 v28, 1.0, v28
	v_add_f32_e32 v29, 1.0, v29
	v_add_f32_e32 v180, 1.0, v180
	v_add_f32_e32 v181, 1.0, v181
	v_rcp_f32_e32 v28, v28
	v_rcp_f32_e32 v29, v29
	v_rcp_f32_e32 v180, v180
	v_rcp_f32_e32 v181, v181
	v_mul_f32_e32 v28, v28, v178
	v_mul_f32_e32 v29, v29, v173
	v_mul_f32_e32 v180, v180, v179
	v_mul_f32_e32 v181, v181, v177
	v_mul_f32_e32 v28, v28, v180
	v_mul_f32_e32 v29, v29, v181
	v_cvt_pk_bf16_f32 v30, v30, v31
	v_cvt_pk_bf16_f32 v31, v32, v33
	v_cvt_pk_bf16_f32 v32, v26, v27
	v_cvt_pk_bf16_f32 v33, v28, v29
	global_store_dwordx4 v[146:147], v[30:33], off
	global_load_dwordx4 v[170:173], v[142:143], off offset:256
	global_load_dwordx4 v[174:177], v[144:145], off offset:256
	s_waitcnt vmcnt(6)
	v_lshlrev_b32_e32 v178, 16, v154
	v_and_b32_e32 v154, 0xffff0000, v154
	v_lshlrev_b32_e32 v179, 16, v158
	v_and_b32_e32 v158, 0xffff0000, v158
	v_mul_f32_e32 v22, 0xbfb8aa3b, v22
	v_mul_f32_e32 v23, 0xbfb8aa3b, v23
	v_mul_f32_e32 v180, 0xbfb8aa3b, v179
	v_mul_f32_e32 v181, 0xbfb8aa3b, v158
	v_exp_f32_e32 v22, v22
	v_exp_f32_e32 v23, v23
	v_exp_f32_e32 v180, v180
	v_exp_f32_e32 v181, v181
	v_add_f32_e32 v22, 1.0, v22
	v_add_f32_e32 v23, 1.0, v23
	v_add_f32_e32 v180, 1.0, v180
	v_add_f32_e32 v181, 1.0, v181
	v_rcp_f32_e32 v22, v22
	v_rcp_f32_e32 v23, v23
	v_rcp_f32_e32 v180, v180
	v_rcp_f32_e32 v181, v181
	v_mul_f32_e32 v22, v22, v178
	v_mul_f32_e32 v23, v23, v154
	v_mul_f32_e32 v180, v180, v179
	v_mul_f32_e32 v181, v181, v158
	v_mul_f32_e32 v22, v22, v180
	v_mul_f32_e32 v23, v23, v181
	v_lshlrev_b32_e32 v178, 16, v155
	v_and_b32_e32 v155, 0xffff0000, v155
	v_lshlrev_b32_e32 v179, 16, v159
	v_and_b32_e32 v159, 0xffff0000, v159
	v_mul_f32_e32 v24, 0xbfb8aa3b, v24
	v_mul_f32_e32 v25, 0xbfb8aa3b, v25
	v_mul_f32_e32 v180, 0xbfb8aa3b, v179
	v_mul_f32_e32 v181, 0xbfb8aa3b, v159
	v_exp_f32_e32 v24, v24
	v_exp_f32_e32 v25, v25
	v_exp_f32_e32 v180, v180
	v_exp_f32_e32 v181, v181
	v_add_f32_e32 v24, 1.0, v24
	v_add_f32_e32 v25, 1.0, v25
	v_add_f32_e32 v180, 1.0, v180
	v_add_f32_e32 v181, 1.0, v181
	v_rcp_f32_e32 v24, v24
	v_rcp_f32_e32 v25, v25
	v_rcp_f32_e32 v180, v180
	v_rcp_f32_e32 v181, v181
	v_mul_f32_e32 v24, v24, v178
	v_mul_f32_e32 v25, v25, v155
	v_mul_f32_e32 v180, v180, v179
	v_mul_f32_e32 v181, v181, v159
	v_mul_f32_e32 v24, v24, v180
	v_mul_f32_e32 v25, v25, v181
	v_lshlrev_b32_e32 v178, 16, v156
	v_and_b32_e32 v156, 0xffff0000, v156
	v_lshlrev_b32_e32 v179, 16, v160
	v_and_b32_e32 v160, 0xffff0000, v160
	v_mul_f32_e32 v18, 0xbfb8aa3b, v18
	v_mul_f32_e32 v19, 0xbfb8aa3b, v19
	v_mul_f32_e32 v180, 0xbfb8aa3b, v179
	v_mul_f32_e32 v181, 0xbfb8aa3b, v160
	v_exp_f32_e32 v18, v18
	v_exp_f32_e32 v19, v19
	v_exp_f32_e32 v180, v180
	v_exp_f32_e32 v181, v181
	v_add_f32_e32 v18, 1.0, v18
	v_add_f32_e32 v19, 1.0, v19
	v_add_f32_e32 v180, 1.0, v180
	v_add_f32_e32 v181, 1.0, v181
	v_rcp_f32_e32 v18, v18
	v_rcp_f32_e32 v19, v19
	v_rcp_f32_e32 v180, v180
	v_rcp_f32_e32 v181, v181
	v_mul_f32_e32 v18, v18, v178
	v_mul_f32_e32 v19, v19, v156
	v_mul_f32_e32 v180, v180, v179
	v_mul_f32_e32 v181, v181, v160
	v_mul_f32_e32 v18, v18, v180
	v_mul_f32_e32 v19, v19, v181
	v_lshlrev_b32_e32 v178, 16, v157
	v_and_b32_e32 v157, 0xffff0000, v157
	v_lshlrev_b32_e32 v179, 16, v161
	v_and_b32_e32 v161, 0xffff0000, v161
	v_mul_f32_e32 v20, 0xbfb8aa3b, v20
	v_mul_f32_e32 v21, 0xbfb8aa3b, v21
	v_mul_f32_e32 v180, 0xbfb8aa3b, v179
	v_mul_f32_e32 v181, 0xbfb8aa3b, v161
	v_exp_f32_e32 v20, v20
	v_exp_f32_e32 v21, v21
	v_exp_f32_e32 v180, v180
	v_exp_f32_e32 v181, v181
	v_add_f32_e32 v20, 1.0, v20
	v_add_f32_e32 v21, 1.0, v21
	v_add_f32_e32 v180, 1.0, v180
	v_add_f32_e32 v181, 1.0, v181
	v_rcp_f32_e32 v20, v20
	v_rcp_f32_e32 v21, v21
	v_rcp_f32_e32 v180, v180
	v_rcp_f32_e32 v181, v181
	v_mul_f32_e32 v20, v20, v178
	v_mul_f32_e32 v21, v21, v157
	v_mul_f32_e32 v180, v180, v179
	v_mul_f32_e32 v181, v181, v161
	v_mul_f32_e32 v20, v20, v180
	v_mul_f32_e32 v21, v21, v181
	v_cvt_pk_bf16_f32 v22, v22, v23
	v_cvt_pk_bf16_f32 v23, v24, v25
	v_cvt_pk_bf16_f32 v24, v18, v19
	v_cvt_pk_bf16_f32 v25, v20, v21
	global_store_dwordx4 v[146:147], v[22:25], off offset:256
	s_mov_b64 s[58:59], 0x20000
	v_lshl_add_u64 v[146:147], v[146:147], 0, s[58:59]
	s_waitcnt vmcnt(4)
	v_lshlrev_b32_e32 v178, 16, v162
	v_and_b32_e32 v162, 0xffff0000, v162
	v_lshlrev_b32_e32 v179, 16, v166
	v_and_b32_e32 v166, 0xffff0000, v166
	v_mul_f32_e32 v14, 0xbfb8aa3b, v14
	v_mul_f32_e32 v15, 0xbfb8aa3b, v15
	v_mul_f32_e32 v180, 0xbfb8aa3b, v179
	v_mul_f32_e32 v181, 0xbfb8aa3b, v166
	v_exp_f32_e32 v14, v14
	v_exp_f32_e32 v15, v15
	v_exp_f32_e32 v180, v180
	v_exp_f32_e32 v181, v181
	v_add_f32_e32 v14, 1.0, v14
	v_add_f32_e32 v15, 1.0, v15
	v_add_f32_e32 v180, 1.0, v180
	v_add_f32_e32 v181, 1.0, v181
	v_rcp_f32_e32 v14, v14
	v_rcp_f32_e32 v15, v15
	v_rcp_f32_e32 v180, v180
	v_rcp_f32_e32 v181, v181
	v_mul_f32_e32 v14, v14, v178
	v_mul_f32_e32 v15, v15, v162
	v_mul_f32_e32 v180, v180, v179
	v_mul_f32_e32 v181, v181, v166
	v_mul_f32_e32 v14, v14, v180
	v_mul_f32_e32 v15, v15, v181
	v_lshlrev_b32_e32 v178, 16, v163
	v_and_b32_e32 v163, 0xffff0000, v163
	v_lshlrev_b32_e32 v179, 16, v167
	v_and_b32_e32 v167, 0xffff0000, v167
	v_mul_f32_e32 v16, 0xbfb8aa3b, v16
	v_mul_f32_e32 v17, 0xbfb8aa3b, v17
	v_mul_f32_e32 v180, 0xbfb8aa3b, v179
	v_mul_f32_e32 v181, 0xbfb8aa3b, v167
	v_exp_f32_e32 v16, v16
	v_exp_f32_e32 v17, v17
	v_exp_f32_e32 v180, v180
	v_exp_f32_e32 v181, v181
	v_add_f32_e32 v16, 1.0, v16
	v_add_f32_e32 v17, 1.0, v17
	v_add_f32_e32 v180, 1.0, v180
	v_add_f32_e32 v181, 1.0, v181
	v_rcp_f32_e32 v16, v16
	v_rcp_f32_e32 v17, v17
	v_rcp_f32_e32 v180, v180
	v_rcp_f32_e32 v181, v181
	v_mul_f32_e32 v16, v16, v178
	v_mul_f32_e32 v17, v17, v163
	v_mul_f32_e32 v180, v180, v179
	v_mul_f32_e32 v181, v181, v167
	v_mul_f32_e32 v16, v16, v180
	v_mul_f32_e32 v17, v17, v181
	v_lshlrev_b32_e32 v178, 16, v164
	v_and_b32_e32 v164, 0xffff0000, v164
	v_lshlrev_b32_e32 v179, 16, v168
	v_and_b32_e32 v168, 0xffff0000, v168
	v_mul_f32_e32 v10, 0xbfb8aa3b, v10
	v_mul_f32_e32 v11, 0xbfb8aa3b, v11
	v_mul_f32_e32 v180, 0xbfb8aa3b, v179
	v_mul_f32_e32 v181, 0xbfb8aa3b, v168
	v_exp_f32_e32 v10, v10
	v_exp_f32_e32 v11, v11
	v_exp_f32_e32 v180, v180
	v_exp_f32_e32 v181, v181
	v_add_f32_e32 v10, 1.0, v10
	v_add_f32_e32 v11, 1.0, v11
	v_add_f32_e32 v180, 1.0, v180
	v_add_f32_e32 v181, 1.0, v181
	v_rcp_f32_e32 v10, v10
	v_rcp_f32_e32 v11, v11
	v_rcp_f32_e32 v180, v180
	v_rcp_f32_e32 v181, v181
	v_mul_f32_e32 v10, v10, v178
	v_mul_f32_e32 v11, v11, v164
	v_mul_f32_e32 v180, v180, v179
	v_mul_f32_e32 v181, v181, v168
	v_mul_f32_e32 v10, v10, v180
	v_mul_f32_e32 v11, v11, v181
	v_lshlrev_b32_e32 v178, 16, v165
	v_and_b32_e32 v165, 0xffff0000, v165
	v_lshlrev_b32_e32 v179, 16, v169
	v_and_b32_e32 v169, 0xffff0000, v169
	v_mul_f32_e32 v12, 0xbfb8aa3b, v12
	v_mul_f32_e32 v13, 0xbfb8aa3b, v13
	v_mul_f32_e32 v180, 0xbfb8aa3b, v179
	v_mul_f32_e32 v181, 0xbfb8aa3b, v169
	v_exp_f32_e32 v12, v12
	v_exp_f32_e32 v13, v13
	v_exp_f32_e32 v180, v180
	v_exp_f32_e32 v181, v181
	v_add_f32_e32 v12, 1.0, v12
	v_add_f32_e32 v13, 1.0, v13
	v_add_f32_e32 v180, 1.0, v180
	v_add_f32_e32 v181, 1.0, v181
	v_rcp_f32_e32 v12, v12
	v_rcp_f32_e32 v13, v13
	v_rcp_f32_e32 v180, v180
	v_rcp_f32_e32 v181, v181
	v_mul_f32_e32 v12, v12, v178
	v_mul_f32_e32 v13, v13, v165
	v_mul_f32_e32 v180, v180, v179
	v_mul_f32_e32 v181, v181, v169
	v_mul_f32_e32 v12, v12, v180
	v_mul_f32_e32 v13, v13, v181
	v_cvt_pk_bf16_f32 v14, v14, v15
	v_cvt_pk_bf16_f32 v15, v16, v17
	v_cvt_pk_bf16_f32 v16, v10, v11
	v_cvt_pk_bf16_f32 v17, v12, v13
	global_store_dwordx4 v[146:147], v[14:17], off
	s_waitcnt vmcnt(2)
	v_lshlrev_b32_e32 v178, 16, v170
	v_and_b32_e32 v170, 0xffff0000, v170
	v_lshlrev_b32_e32 v179, 16, v174
	v_and_b32_e32 v174, 0xffff0000, v174
	v_mul_f32_e32 v6, 0xbfb8aa3b, v6
	v_mul_f32_e32 v7, 0xbfb8aa3b, v7
	v_mul_f32_e32 v180, 0xbfb8aa3b, v179
	v_mul_f32_e32 v181, 0xbfb8aa3b, v174
	v_exp_f32_e32 v6, v6
	v_exp_f32_e32 v7, v7
	v_exp_f32_e32 v180, v180
	v_exp_f32_e32 v181, v181
	v_add_f32_e32 v6, 1.0, v6
	v_add_f32_e32 v7, 1.0, v7
	v_add_f32_e32 v180, 1.0, v180
	v_add_f32_e32 v181, 1.0, v181
	v_rcp_f32_e32 v6, v6
	v_rcp_f32_e32 v7, v7
	v_rcp_f32_e32 v180, v180
	v_rcp_f32_e32 v181, v181
	v_mul_f32_e32 v6, v6, v178
	v_mul_f32_e32 v7, v7, v170
	v_mul_f32_e32 v180, v180, v179
	v_mul_f32_e32 v181, v181, v174
	v_mul_f32_e32 v6, v6, v180
	v_mul_f32_e32 v7, v7, v181
	v_lshlrev_b32_e32 v178, 16, v171
	v_and_b32_e32 v171, 0xffff0000, v171
	v_lshlrev_b32_e32 v179, 16, v175
	v_and_b32_e32 v175, 0xffff0000, v175
	v_mul_f32_e32 v8, 0xbfb8aa3b, v8
	v_mul_f32_e32 v9, 0xbfb8aa3b, v9
	v_mul_f32_e32 v180, 0xbfb8aa3b, v179
	v_mul_f32_e32 v181, 0xbfb8aa3b, v175
	v_exp_f32_e32 v8, v8
	v_exp_f32_e32 v9, v9
	v_exp_f32_e32 v180, v180
	v_exp_f32_e32 v181, v181
	v_add_f32_e32 v8, 1.0, v8
	v_add_f32_e32 v9, 1.0, v9
	v_add_f32_e32 v180, 1.0, v180
	v_add_f32_e32 v181, 1.0, v181
	v_rcp_f32_e32 v8, v8
	v_rcp_f32_e32 v9, v9
	v_rcp_f32_e32 v180, v180
	v_rcp_f32_e32 v181, v181
	v_mul_f32_e32 v8, v8, v178
	v_mul_f32_e32 v9, v9, v171
	v_mul_f32_e32 v180, v180, v179
	v_mul_f32_e32 v181, v181, v175
	v_mul_f32_e32 v8, v8, v180
	v_mul_f32_e32 v9, v9, v181
	v_lshlrev_b32_e32 v178, 16, v172
	v_and_b32_e32 v172, 0xffff0000, v172
	v_lshlrev_b32_e32 v179, 16, v176
	v_and_b32_e32 v176, 0xffff0000, v176
	v_mul_f32_e32 v2, 0xbfb8aa3b, v2
	v_mul_f32_e32 v3, 0xbfb8aa3b, v3
	v_mul_f32_e32 v180, 0xbfb8aa3b, v179
	v_mul_f32_e32 v181, 0xbfb8aa3b, v176
	v_exp_f32_e32 v2, v2
	v_exp_f32_e32 v3, v3
	v_exp_f32_e32 v180, v180
	v_exp_f32_e32 v181, v181
	v_add_f32_e32 v2, 1.0, v2
	v_add_f32_e32 v3, 1.0, v3
	v_add_f32_e32 v180, 1.0, v180
	v_add_f32_e32 v181, 1.0, v181
	v_rcp_f32_e32 v2, v2
	v_rcp_f32_e32 v3, v3
	v_rcp_f32_e32 v180, v180
	v_rcp_f32_e32 v181, v181
	v_mul_f32_e32 v2, v2, v178
	v_mul_f32_e32 v3, v3, v172
	v_mul_f32_e32 v180, v180, v179
	v_mul_f32_e32 v181, v181, v176
	v_mul_f32_e32 v2, v2, v180
	v_mul_f32_e32 v3, v3, v181
	v_lshlrev_b32_e32 v178, 16, v173
	v_and_b32_e32 v173, 0xffff0000, v173
	v_lshlrev_b32_e32 v179, 16, v177
	v_and_b32_e32 v177, 0xffff0000, v177
	v_mul_f32_e32 v4, 0xbfb8aa3b, v4
	v_mul_f32_e32 v5, 0xbfb8aa3b, v5
	v_mul_f32_e32 v180, 0xbfb8aa3b, v179
	v_mul_f32_e32 v181, 0xbfb8aa3b, v177
	v_exp_f32_e32 v4, v4
	v_exp_f32_e32 v5, v5
	v_exp_f32_e32 v180, v180
	v_exp_f32_e32 v181, v181
	v_add_f32_e32 v4, 1.0, v4
	v_add_f32_e32 v5, 1.0, v5
	v_add_f32_e32 v180, 1.0, v180
	v_add_f32_e32 v181, 1.0, v181
	v_rcp_f32_e32 v4, v4
	v_rcp_f32_e32 v5, v5
	v_rcp_f32_e32 v180, v180
	v_rcp_f32_e32 v181, v181
	v_mul_f32_e32 v4, v4, v178
	v_mul_f32_e32 v5, v5, v173
	v_mul_f32_e32 v180, v180, v179
	v_mul_f32_e32 v181, v181, v177
	v_mul_f32_e32 v4, v4, v180
	v_mul_f32_e32 v5, v5, v181
	v_cvt_pk_bf16_f32 v6, v6, v7
	v_cvt_pk_bf16_f32 v7, v8, v9
	v_cvt_pk_bf16_f32 v8, v2, v3
	v_cvt_pk_bf16_f32 v9, v4, v5
	global_store_dwordx4 v[146:147], v[6:9], off offset:256
	s_andn2_b64 vcc, exec, s[38:39]
	s_mov_b64 s[4:5], -1
	s_cbranch_vccnz .LBB0_686
	s_andn2_b64 vcc, exec, s[42:43]
	s_cbranch_vccnz .LBB0_685
	s_barrier
	s_branch .LBB0_685
	s_nop 0
	s_nop 0
	s_nop 0
	s_nop 0
	s_nop 0
	s_nop 0
	s_nop 0
	s_nop 0
	s_nop 0
	s_nop 0
	s_nop 0
	s_nop 0
	s_nop 0
	s_nop 0
	s_nop 0
	s_nop 0
	s_nop 0
	s_nop 0
	s_nop 0
	s_nop 0
	s_nop 0
	s_nop 0
	s_nop 0
	s_nop 0
	s_nop 0
	s_nop 0
	s_nop 0
	s_nop 0
	s_nop 0
	s_nop 0
.LBB0_698:
	v_readlane_b32 s60, v255, 0
	s_waitcnt vmcnt(0)
	v_readlane_b32 s61, v255, 1
	v_readlane_b32 s70, v254, 62
	v_readlane_b32 s60, v255, 6
	v_readlane_b32 s71, v254, 63
	v_readlane_b32 s62, v255, 2
	v_readlane_b32 s63, v255, 3
	v_readlane_b32 s61, v255, 7
	s_barrier

.LBB0_786:
	s_waitcnt vmcnt(0)
	s_waitcnt vmcnt(0)
	s_barrier
	v_readlane_b32 s0, v255, 8
	s_nop 3
	s_cmp_lg_u32 s0, 0
	s_cbranch_scc1 .Lmy_seam7_full
	s_branch .Lmy_tr10_a
.Lmy_seam7_full:
	s_mov_b64 s[4:5], exec
	v_readlane_b32 s6, v254, 56
	v_readlane_b32 s7, v254, 57
	s_and_b64 s[6:7], s[4:5], s[6:7]
	s_mov_b64 exec, s[6:7]
	s_cbranch_execnz .LBB0_787
	s_getpc_b64 s[98:99]
